# attention K/V fragments via per-wave LDS-DMA + ds_read; conv loads batched with hoisted tap weights; merged V loads; single 16B slot load
# speedup vs baseline: 1.0044x; 1.0044x over previous
; __device__ __forceinline__ int tid_opaque() { int t = threadIdx.x; asm volatile("" : "+v"(t)); return t; }
; __device__ __forceinline__ void attn_item(const Params& p, int l, int hs, int idx) {
;     const int tid = tid_opaque(), wid = __builtin_amdgcn_readfirstlane(tid >> 6), lane = tid & 63, fr = lane & 15, fq = lane >> 4;
;     const bf16_t* P = (const bf16_t*)(p.ws + WS_R1);
;     const bf16_t* VTL = (const bf16_t*)(p.ws + WS_VTL); const bf16_t* VTC = (const bf16_t*)(p.ws + WS_VTC);
;     bf16_t* Y = (bf16_t*)(p.ws + WS_A) + (size_t)part_u0(hs) * D;
;     const int latN = part_lat(hs), nli = part_nb(hs) * 32;
;     int bl, qb, hk; bool lat;
;     if (idx < nli) { lat = true; bl = idx >> 5; qb = (idx >> 1) & 15; hk = idx & 1; }
;     else { const int j = idx - nli; lat = false; bl = j >> 2; qb = (j >> 1) & 1; hk = j & 1; }
;     const int g = wid >> 1, r0 = (wid & 1) * 64, head = hk * 4 + g;
;     const int qrow0 = lat ? bl * SEQ + qb * 128 : latN + bl * CTXL + qb * 128;
;     const int crow0 = latN + bl * CTXL;
;     bf16x8 qf[4][2];
;     { const bf16_t* qp = P + (size_t)(qrow0 + r0 + fr) * PROJ + OFF_Q + head * 64 + fq * 8;
; #pragma unroll
;       for (int nq = 0; nq < 4; ++nq)
; #pragma unroll
;           for (int ks = 0; ks < 2; ++ks) qf[nq][ks] = *(const bf16x8*)(qp + (size_t)nq * 16 * PROJ + ks * 32); }
;     f32x4 o[4][4];
; #pragma unroll
;     for (int a = 0; a < 4; ++a)
; #pragma unroll
;         for (int b = 0; b < 4; ++b) o[a][b] = (f32x4){0.f, 0.f, 0.f, 0.f};
;     const float snk = p.in[I_SINK][l * 8 + head] * LOG2E;
;     float mrun[4], lrun[4];
; #pragma unroll
;     for (int nq = 0; nq < 4; ++nq) { mrun[nq] = snk; lrun[nq] = (fq == 0) ? 1.0f : 0.0f; }
;     int lo = 0, nb = 0;
;     if (lat) { lo = (qb == 0) ? 4 : (r0 >> 5); const int hi = (qb == 15) ? 8 : (r0 == 0 ? 10 : 12); nb = hi - lo; }
.LBB0_144:
	s_and_b32 s5, s41, 1
	v_and_b32_e32 v19, 15, v18
	s_lshl_b32 s28, s8, 8
	s_addk_i32 s28, 0x1000
	v_and_b32_e32 v216, 63, v18
	v_lshl_add_u32 v216, v216, 4, s28
	s_ashr_i32 s12, s8, 7
	s_and_b32 s8, s8, 64
	s_lshl_b32 s13, s5, 2
	s_add_i32 s16, s12, s13
	v_or_b32_e32 v0, s8, v19
	v_add_u32_e32 v184, s11, v0
	s_waitcnt vmcnt(0)
	v_mov_b64_e32 v[2:3], s[52:53]
	s_lshl_b32 s14, s16, 6
	v_mad_i64_i32 v[2:3], s[12:13], v184, s97, v[2:3]
	s_ashr_i32 s15, s14, 31
	v_lshl_add_u64 v[2:3], s[14:15], 1, v[2:3]
	v_and_b32_e32 v0, 48, v18
	v_lshl_add_u64 v[2:3], v[2:3], 0, v[0:1]
	v_add_co_u32_e32 v4, vcc, s51, v2
	v_readlane_b32 s11, v255, 4
	s_nop 0
	v_addc_co_u32_e32 v5, vcc, 0, v3, vcc
	s_add_i32 s12, s16, s11
	global_load_dwordx4 v[20:23], v[2:3], off offset:2560
	global_load_dwordx4 v[24:27], v[2:3], off offset:2624
	global_load_dwordx4 v[28:31], v[4:5], off offset:2560
	global_load_dwordx4 v[32:35], v[4:5], off offset:2624
	v_add_co_u32_e32 v4, vcc, s96, v2
	s_ashr_i32 s13, s12, 31
	s_nop 0
	v_addc_co_u32_e32 v5, vcc, 0, v3, vcc
	s_lshl_b64 s[12:13], s[12:13], 2
	v_add_co_u32_e32 v2, vcc, s17, v2
	s_add_u32 s12, s72, s12
	s_nop 0
	v_addc_co_u32_e32 v3, vcc, 0, v3, vcc
	s_addc_u32 s13, s73, s13
	global_load_dwordx4 v[36:39], v[4:5], off offset:2560
	global_load_dwordx4 v[40:43], v[4:5], off offset:2624
	global_load_dwordx4 v[44:47], v[2:3], off offset:2560
	global_load_dwordx4 v[48:51], v[2:3], off offset:2624
	global_load_dword v52, v1, s[12:13]
	s_mov_b32 s40, 0
	s_andn2_b64 vcc, exec, s[0:1]
	s_mov_b32 s37, 0
	s_cbranch_vccnz .LBB0_146
	s_lshr_b32 s11, s8, 5
	s_cmp_lg_u32 s9, 0
	s_cselect_b32 s37, s11, 4
	s_cmp_eq_u32 s8, 0
	s_cselect_b32 s11, 10, 12
	s_cmp_lg_u32 s9, 15
	s_cselect_b32 s9, s11, 8
	s_sub_i32 s40, s9, s37

; __device__ __forceinline__ void attn_item(const Params& p, int l, int hs, int idx) {
;     ...
;     f32x4 o[4][4];
; #pragma unroll
;     for (int a = 0; a < 4; ++a)
; #pragma unroll
;         for (int b = 0; b < 4; ++b) o[a][b] = (f32x4){0.f, 0.f, 0.f, 0.f};
;     const float snk = p.in[I_SINK][l * 8 + head] * LOG2E;
;     float mrun[4], lrun[4];
; #pragma unroll
;     for (int nq = 0; nq < 4; ++nq) { mrun[nq] = snk; lrun[nq] = (fq == 0) ? 1.0f : 0.0f; }
.LBB0_151:
	s_add_i32 s36, s40, 8
	s_add_u32 s6, s52, s6
	v_lshrrev_b32_e32 v0, 2, v19
	v_lshlrev_b32_e32 v0, 3, v0
	v_and_or_b32 v0, v19, 3, v0
	v_mul_u32_u24_e32 v0, 0x1400, v0
	s_addc_u32 s7, s53, s7
	s_lshl_b32 s10, s11, 1
	v_or_b32_e32 v0, v54, v0
	s_add_u32 s6, s6, s10
	v_lshlrev_b32_e32 v0, 1, v0
	s_addc_u32 s7, s7, 0
	s_add_i32 m0, s28, 4096
	s_nop 0
	global_load_lds_dwordx4 v[2:3], off
	s_add_i32 m0, s28, 5120
	s_nop 0
	global_load_lds_dwordx4 v[6:7], off
	s_add_i32 m0, s28, 6144
	s_nop 0
	global_load_lds_dwordx4 v[10:11], off
	s_add_i32 m0, s28, 7168
	s_nop 0
	global_load_lds_dwordx4 v[14:15], off
	s_add_i32 m0, s28, -3584
	s_nop 0
	global_load_lds_dwordx4 v0, s[6:7] offset:3584
	s_add_i32 m0, s28, -2624
	s_nop 0
	global_load_lds_dwordx4 v0, s[6:7] offset:3648
	v_lshl_add_u64 v[54:55], s[6:7], 0, v[0:1]
	v_add_co_u32_e32 v2, vcc, 0xa000, v54
	s_nop 1
	v_addc_co_u32_e32 v3, vcc, 0, v55, vcc
	s_add_i32 m0, s28, -1536
	s_nop 0
	global_load_lds_dwordx4 v[2:3], off offset:3584
	s_add_i32 m0, s28, -576
	s_nop 0
	global_load_lds_dwordx4 v[2:3], off offset:3648
	s_add_u32 s6, s52, s10
	v_and_b32_e32 v2, 63, v18
	v_lshlrev_b32_e32 v201, 2, v53
	s_addc_u32 s7, s53, 0
	s_addk_i32 s9, 0xfecf
	v_cmp_gt_u32_e32 vcc, 16, v2
	v_lshlrev_b32_e32 v2, 2, v2
	v_lshl_add_u64 v[192:193], s[6:7], 0, v[0:1]
	v_lshl_add_u32 v0, v53, 3, s9
	v_cndmask_b32_e64 v186, 0, 1.0, vcc
	v_xor_b32_e32 v199, 64, v2
	v_xor_b32_e32 v195, 0x80, v2
	v_sub_u32_e32 v0, v0, v19
	v_mov_b32_e32 v2, v1
	v_mov_b32_e32 v3, v1
	s_waitcnt vmcnt(0)
	v_mul_f32_e32 v202, 0x3fb8aa3b, v52
	v_mov_b32_e32 v187, v186
	v_subrev_u32_e32 v207, s8, v0
	v_mov_b32_e32 v0, v1
	v_mov_b64_e32 v[10:11], v[2:3]
	v_mov_b64_e32 v[54:55], v[2:3]
	v_mov_b64_e32 v[82:83], v[2:3]
	v_mov_b64_e32 v[118:119], v[2:3]
	v_mov_b64_e32 v[6:7], v[2:3]
	v_mov_b64_e32 v[58:59], v[2:3]
	v_mov_b64_e32 v[98:99], v[2:3]
	v_mov_b64_e32 v[130:131], v[2:3]
	v_mov_b64_e32 v[122:123], v[2:3]
	v_mov_b64_e32 v[90:91], v[2:3]
	v_mov_b64_e32 v[62:63], v[2:3]
	v_mov_b64_e32 v[14:15], v[2:3]
	v_mov_b64_e32 v[126:127], v[2:3]
	v_mov_b64_e32 v[102:103], v[2:3]
	v_mov_b64_e32 v[66:67], v[2:3]
	v_mov_b64_e32 v[18:19], v[2:3]
	v_ashrrev_i32_e32 v185, 31, v184
	s_mov_b32 s38, 0
	v_mov_b64_e32 v[8:9], v[0:1]
	v_mov_b64_e32 v[52:53], v[0:1]
	v_mov_b64_e32 v[80:81], v[0:1]
	v_mov_b64_e32 v[116:117], v[0:1]
	v_mov_b64_e32 v[4:5], v[0:1]
	v_mov_b64_e32 v[56:57], v[0:1]
	v_mov_b64_e32 v[96:97], v[0:1]
	v_mov_b64_e32 v[128:129], v[0:1]
	v_mov_b32_e32 v198, v202
	v_mov_b32_e32 v196, v202
	v_mov_b32_e32 v194, v202
	v_mov_b64_e32 v[120:121], v[0:1]
	v_mov_b64_e32 v[88:89], v[0:1]
	v_mov_b64_e32 v[60:61], v[0:1]
	v_mov_b64_e32 v[12:13], v[0:1]
	v_mov_b64_e32 v[124:125], v[0:1]
	v_mov_b64_e32 v[100:101], v[0:1]
	v_mov_b64_e32 v[64:65], v[0:1]
	v_mov_b64_e32 v[16:17], v[0:1]
	v_mov_b64_e32 v[2:3], v[186:187]

; __device__ __forceinline__ void attn_item(const Params& p, int l, int hs, int idx) {
;     ...
;         ATT_LOAD(i1, kfb, vlb, vhb);
;         ATT_COMPUTE(i, kfa, vla, vha);
.LBB0_155:
	s_waitcnt vmcnt(0)
	ds_read_b128 v[144:147], v216
	ds_read_b128 v[140:143], v216 offset:1024
	ds_read_b128 v[136:139], v216 offset:2048
	ds_read_b128 v[132:135], v216 offset:3072
	ds_read_b128 v[84:87], v216 offset:4096
	ds_read_b128 v[76:79], v216 offset:5120
	ds_read_b128 v[72:75], v216 offset:6144
	ds_read_b128 v[68:71], v216 offset:7168
	s_waitcnt lgkmcnt(4)
	v_mfma_f32_16x16x32_bf16 v[104:107], v[144:147], v[20:23], 0
	s_lshl_b32 s25, s24, 6
	s_add_u32 s20, s20, s25
	s_addc_u32 s21, s21, 0
	v_mfma_f32_16x16x32_bf16 v[176:179], v[140:143], v[24:27], v[104:107]
	s_add_u32 s18, s20, s18
	s_addc_u32 s19, s21, s19
	s_add_u32 s16, s20, s16
	v_mfma_f32_16x16x32_bf16 v[104:107], v[144:147], v[28:31], 0
	s_addc_u32 s17, s21, s17
	s_add_u32 s12, s20, s12
	s_addc_u32 s13, s21, s13
	v_mfma_f32_16x16x32_bf16 v[168:171], v[140:143], v[32:35], v[104:107]
	s_add_u32 s10, s20, s10
	s_addc_u32 s11, s21, s11
	s_add_u32 s8, s20, s8
	v_mfma_f32_16x16x32_bf16 v[104:107], v[144:147], v[36:39], 0
	s_addc_u32 s9, s21, s9
	s_add_u32 s6, s20, s6
	v_lshl_add_u64 v[94:95], v[192:193], 0, s[22:23]
	v_mfma_f32_16x16x32_bf16 v[164:167], v[140:143], v[40:43], v[104:107]
	s_addc_u32 s7, s21, s7
	v_mad_u64_u32 v[148:149], s[22:23], s24, v226, v[94:95]
	v_mfma_f32_16x16x32_bf16 v[104:107], v[144:147], v[44:47], 0
	v_lshl_add_u64 v[94:95], s[20:21], 0, v[92:93]
	v_lshl_add_u64 v[108:109], s[18:19], 0, v[92:93]
	v_lshl_add_u64 v[110:111], s[16:17], 0, v[92:93]
	v_mfma_f32_16x16x32_bf16 v[140:143], v[140:143], v[48:51], v[104:107]
	v_lshl_add_u64 v[150:151], s[12:13], 0, v[92:93]
	v_lshl_add_u64 v[152:153], s[10:11], 0, v[92:93]
	v_lshl_add_u64 v[154:155], s[8:9], 0, v[92:93]
	v_mfma_f32_16x16x32_bf16 v[104:107], v[136:139], v[20:23], 0
	v_lshl_add_u64 v[92:93], s[6:7], 0, v[92:93]
	s_add_i32 m0, s28, 13312
	s_nop 0
	global_load_lds_dwordx4 v[108:109], off
	s_add_i32 m0, s28, 12288
	s_nop 0
	global_load_lds_dwordx4 v[94:95], off
	s_add_i32 s44, s37, s38
	v_mfma_f32_16x16x32_bf16 v[180:183], v[132:135], v[24:27], v[104:107]
	s_nop 2
	s_add_i32 m0, s28, 15360
	s_nop 0
	global_load_lds_dwordx4 v[154:155], off
	s_add_i32 m0, s28, 14336
	s_nop 0
	global_load_lds_dwordx4 v[150:151], off
	s_add_i32 m0, s28, 4608
	s_nop 0
	global_load_lds_dwordx4 v[148:149], off offset:3584
	s_add_i32 m0, s28, 5568
	s_nop 0
	global_load_lds_dwordx4 v[148:149], off offset:3648
	v_add_co_u32_e32 v148, vcc, 0xa000, v148
	v_mfma_f32_16x16x32_bf16 v[144:147], v[136:139], v[28:31], 0
	s_nop 0
	v_addc_co_u32_e32 v149, vcc, 0, v149, vcc
	s_add_i32 m0, s28, 6656
	s_nop 0
	global_load_lds_dwordx4 v[148:149], off offset:3584
	s_add_i32 m0, s28, 7616
	s_nop 0
	global_load_lds_dwordx4 v[148:149], off offset:3648
	v_mfma_f32_16x16x32_bf16 v[172:175], v[132:135], v[32:35], v[144:147]
	s_add_i32 s6, s44, -8
	s_cmp_lt_u32 s6, -4
	s_cselect_b64 s[6:7], -1, 0
	v_mfma_f32_16x16x32_bf16 v[144:147], v[136:139], v[36:39], 0
	s_cmp_lt_u32 s38, s40
	s_cselect_b64 s[8:9], -1, 0
	s_and_b64 s[6:7], s[8:9], s[6:7]
	v_mfma_f32_16x16x32_bf16 v[136:139], v[136:139], v[44:47], 0
	s_andn2_b64 vcc, exec, s[6:7]
	v_add_u32_e32 v205, 64, v207
	v_mfma_f32_16x16x32_bf16 v[144:147], v[132:135], v[40:43], v[144:147]
	v_mfma_f32_16x16x32_bf16 v[132:135], v[132:135], v[48:51], v[136:139]
	s_cbranch_vccnz .LBB0_157
	v_add_u32_e32 v0, 48, v207
	v_cmp_gt_u32_e64 s[6:7], s93, v0
	v_add_u32_e32 v0, 49, v207
	v_cmp_gt_u32_e64 s[8:9], s93, v0
	v_add_u32_e32 v0, 50, v207
	v_cmp_gt_u32_e64 s[10:11], s93, v0
	v_add_u32_e32 v0, 51, v207
	v_cmp_gt_u32_e64 s[12:13], s93, v0
	s_nop 1
	v_cndmask_b32_e64 v176, v176, v227, s[6:7]
	v_cndmask_b32_e64 v177, v177, v227, s[8:9]
	v_cndmask_b32_e64 v178, v178, v227, s[10:11]
	v_cndmask_b32_e64 v179, v179, v227, s[12:13]
	v_add_u32_e32 v0, 32, v207
	v_cmp_gt_u32_e64 s[6:7], s93, v0
	v_add_u32_e32 v0, 33, v207
	v_cmp_gt_u32_e64 s[8:9], s93, v0
	v_add_u32_e32 v0, 34, v207
	v_cmp_gt_u32_e64 s[10:11], s93, v0
	v_add_u32_e32 v0, 35, v207
	v_cmp_gt_u32_e64 s[12:13], s93, v0
	s_nop 1
	v_cndmask_b32_e64 v168, v168, v227, s[6:7]
	v_cndmask_b32_e64 v169, v169, v227, s[8:9]
	v_cndmask_b32_e64 v170, v170, v227, s[10:11]
	v_cndmask_b32_e64 v171, v171, v227, s[12:13]
	v_add_u32_e32 v0, 16, v207
	v_cmp_gt_u32_e64 s[6:7], s93, v0
	v_add_u32_e32 v0, 17, v207
	v_cmp_gt_u32_e64 s[8:9], s93, v0
	v_add_u32_e32 v0, 18, v207
	v_cmp_gt_u32_e64 s[10:11], s93, v0
	v_add_u32_e32 v0, 19, v207
	v_cmp_gt_u32_e64 s[12:13], s93, v0
	s_nop 1
	v_cndmask_b32_e64 v164, v164, v227, s[6:7]
	v_cndmask_b32_e64 v165, v165, v227, s[8:9]
	v_cndmask_b32_e64 v166, v166, v227, s[10:11]
	v_cndmask_b32_e64 v167, v167, v227, s[12:13]
	v_add_u32_e32 v0, 0, v207
	v_cmp_gt_u32_e64 s[6:7], s93, v0
	v_add_u32_e32 v0, 1, v207
	v_cmp_gt_u32_e64 s[8:9], s93, v0
	v_add_u32_e32 v0, 2, v207
	v_cmp_gt_u32_e64 s[10:11], s93, v0
	v_add_u32_e32 v0, 3, v207
	v_cmp_gt_u32_e64 s[12:13], s93, v0
	s_nop 1
	v_cndmask_b32_e64 v140, v140, v227, s[6:7]
	v_cndmask_b32_e64 v141, v141, v227, s[8:9]
	v_cndmask_b32_e64 v142, v142, v227, s[10:11]
	v_cndmask_b32_e64 v143, v143, v227, s[12:13]
	v_add_u32_e32 v0, 52, v207
	v_cmp_gt_u32_e64 s[6:7], s93, v0
	v_add_u32_e32 v0, 53, v207
	v_cmp_gt_u32_e64 s[8:9], s93, v0
	v_add_u32_e32 v0, 54, v207
	v_cmp_gt_u32_e64 s[10:11], s93, v0
	v_add_u32_e32 v0, 55, v207
	v_cmp_gt_u32_e64 s[12:13], s93, v0
	s_nop 1
	v_cndmask_b32_e64 v180, v180, v227, s[6:7]
	v_cndmask_b32_e64 v181, v181, v227, s[8:9]
	v_cndmask_b32_e64 v182, v182, v227, s[10:11]
	v_cndmask_b32_e64 v183, v183, v227, s[12:13]
	v_add_u32_e32 v0, 36, v207
	v_cmp_gt_u32_e64 s[6:7], s93, v0
	v_add_u32_e32 v0, 37, v207
	v_cmp_gt_u32_e64 s[8:9], s93, v0
	v_add_u32_e32 v0, 38, v207
	v_cmp_gt_u32_e64 s[10:11], s93, v0
	v_add_u32_e32 v0, 39, v207
	v_cmp_gt_u32_e64 s[12:13], s93, v0
	s_nop 1
	v_cndmask_b32_e64 v172, v172, v227, s[6:7]
	v_cndmask_b32_e64 v173, v173, v227, s[8:9]
	v_cndmask_b32_e64 v174, v174, v227, s[10:11]
	v_cndmask_b32_e64 v175, v175, v227, s[12:13]
	v_add_u32_e32 v0, 20, v207
	v_cmp_gt_u32_e64 s[6:7], s93, v0
	v_add_u32_e32 v0, 21, v207
	v_cmp_gt_u32_e64 s[8:9], s93, v0
	v_add_u32_e32 v0, 22, v207
	v_cmp_gt_u32_e64 s[10:11], s93, v0
	v_add_u32_e32 v0, 23, v207
	v_cmp_gt_u32_e64 s[12:13], s93, v0
	s_nop 1
	v_cndmask_b32_e64 v144, v144, v227, s[6:7]
	v_cndmask_b32_e64 v145, v145, v227, s[8:9]
	v_cndmask_b32_e64 v146, v146, v227, s[10:11]
	v_cndmask_b32_e64 v147, v147, v227, s[12:13]
	v_add_u32_e32 v0, 4, v207
	v_cmp_gt_u32_e64 s[6:7], s93, v0
	v_add_u32_e32 v0, 5, v207
	v_cmp_gt_u32_e64 s[8:9], s93, v0
	v_add_u32_e32 v0, 6, v207
	v_cmp_gt_u32_e64 s[10:11], s93, v0
	v_add_u32_e32 v0, 7, v207
	v_cmp_gt_u32_e64 s[12:13], s93, v0
	s_nop 1
	v_cndmask_b32_e64 v132, v132, v227, s[6:7]
	v_cndmask_b32_e64 v133, v133, v227, s[8:9]
	v_cndmask_b32_e64 v134, v134, v227, s[10:11]
	v_cndmask_b32_e64 v135, v135, v227, s[12:13]

.LBB0_160:
	s_lshl_b32 s25, s24, 6
	s_add_u32 s20, s20, s25
	v_pk_add_f32 v[70:71], v[176:177], 0 op_sel_hi:[1,0]
	v_pk_add_f32 v[72:73], v[168:169], 0 op_sel_hi:[1,0]
	s_addc_u32 s21, s21, 0
	v_pk_add_f32 v[70:71], v[178:179], v[70:71]
	v_pk_add_f32 v[72:73], v[170:171], v[72:73]
	s_add_u32 s18, s20, s18
	v_pk_add_f32 v[70:71], v[180:181], v[70:71]
	v_pk_add_f32 v[72:73], v[172:173], v[72:73]
	s_addc_u32 s19, s21, s19
	v_pk_add_f32 v[70:71], v[182:183], v[70:71]
	v_pk_add_f32 v[72:73], v[174:175], v[72:73]
	s_add_u32 s16, s20, s16
	v_mov_b32_e32 v74, v72
	v_mov_b32_e32 v75, v70
	v_mov_b32_e32 v70, v73
	s_addc_u32 s17, s21, s17
	v_mov_b32_e32 v197, v194
	v_pk_add_f32 v[70:71], v[74:75], v[70:71]
	s_add_u32 s12, s20, s12
	v_pk_fma_f32 v[2:3], v[2:3], v[196:197], v[70:71]
	v_pk_add_f32 v[70:71], v[164:165], 0 op_sel_hi:[1,0]
	v_pk_add_f32 v[72:73], v[140:141], 0 op_sel_hi:[1,0]
	s_addc_u32 s13, s21, s13
	v_pk_add_f32 v[70:71], v[166:167], v[70:71]
	v_pk_add_f32 v[72:73], v[142:143], v[72:73]
	s_add_u32 s10, s20, s10
	v_pk_add_f32 v[70:71], v[144:145], v[70:71]
	v_pk_add_f32 v[72:73], v[132:133], v[72:73]
	s_addc_u32 s11, s21, s11
	v_pk_add_f32 v[70:71], v[146:147], v[70:71]
	v_pk_add_f32 v[72:73], v[202:203], v[72:73]
	s_add_u32 s8, s20, s8
	v_mov_b32_e32 v74, v72
	v_mov_b32_e32 v75, v70
	v_mov_b32_e32 v70, v73
	s_addc_u32 s9, s21, s9
	v_mov_b32_e32 v135, v198
	v_pk_add_f32 v[70:71], v[74:75], v[70:71]
	s_add_u32 s6, s20, s6
	v_pk_fma_f32 v[186:187], v[186:187], v[134:135], v[70:71]
	v_lshl_add_u64 v[70:71], v[192:193], 0, s[22:23]
	s_addc_u32 s7, s21, s7
	v_mad_u64_u32 v[144:145], s[22:23], s24, v226, v[70:71]
	v_lshl_add_u64 v[72:73], s[20:21], 0, v[68:69]
	v_lshl_add_u64 v[76:77], s[18:19], 0, v[68:69]
	v_lshl_add_u64 v[70:71], s[16:17], 0, v[68:69]
	v_lshl_add_u64 v[132:133], s[12:13], 0, v[68:69]
	v_lshl_add_u64 v[74:75], s[10:11], 0, v[68:69]
	v_lshl_add_u64 v[134:135], s[8:9], 0, v[68:69]
	v_lshl_add_u64 v[68:69], s[6:7], 0, v[68:69]
	s_add_i32 m0, s28, 4096
	s_nop 0
	global_load_lds_dwordx4 v[72:73], off
	s_add_i32 m0, s28, 5120
	s_nop 0
	global_load_lds_dwordx4 v[76:77], off
	s_add_i32 m0, s28, 6144
	s_nop 0
	global_load_lds_dwordx4 v[132:133], off
	s_add_i32 m0, s28, 7168
	s_nop 0
	global_load_lds_dwordx4 v[134:135], off
	v_add_co_u32_e32 v136, vcc, 0xa000, v144
	s_nop 1
	v_addc_co_u32_e32 v137, vcc, 0, v145, vcc
	s_add_i32 m0, s28, -576
	s_nop 0
	global_load_lds_dwordx4 v[136:137], off offset:3648
	s_add_i32 m0, s28, -1536
	s_nop 0
	global_load_lds_dwordx4 v[136:137], off offset:3584
	s_add_i32 m0, s28, -2624
	s_nop 0
	global_load_lds_dwordx4 v[144:145], off offset:3648
	s_add_i32 m0, s28, -3584
	s_nop 0
	global_load_lds_dwordx4 v[144:145], off offset:3584
	s_andn2_b64 vcc, exec, s[34:35]
	s_cbranch_vccnz .LBB0_164
	s_waitcnt vmcnt(8)
	ds_read_b128 v[156:159], v216 offset:8192
	ds_read_b128 v[160:163], v216 offset:9216
	ds_read_b128 v[152:155], v216 offset:10240
	ds_read_b128 v[148:151], v216 offset:11264
	ds_read_b128 v[112:115], v216 offset:12288
	ds_read_b128 v[108:111], v216 offset:13312
	ds_read_b128 v[104:107], v216 offset:14336
	ds_read_b128 v[92:95], v216 offset:15360
	s_waitcnt lgkmcnt(4)
	v_mfma_f32_16x16x32_bf16 v[164:167], v[156:159], v[20:23], 0
	s_add_i32 s44, s44, -7
	s_cmp_lt_u32 s44, -4
	s_cselect_b64 s[6:7], -1, 0
	s_waitcnt vmcnt(10)
	v_mfma_f32_16x16x32_bf16 v[180:183], v[160:163], v[24:27], v[164:167]
	s_cmp_lt_u32 s42, s40
	s_cselect_b64 s[8:9], -1, 0
	s_and_b64 s[6:7], s[8:9], s[6:7]
	v_mfma_f32_16x16x32_bf16 v[164:167], v[156:159], v[28:31], 0
	s_andn2_b64 vcc, exec, s[6:7]
	v_mfma_f32_16x16x32_bf16 v[172:175], v[160:163], v[32:35], v[164:167]
	v_mfma_f32_16x16x32_bf16 v[164:167], v[156:159], v[36:39], 0
	v_mfma_f32_16x16x32_bf16 v[156:159], v[156:159], v[44:47], 0
	v_mfma_f32_16x16x32_bf16 v[168:171], v[160:163], v[40:43], v[164:167]
	v_mfma_f32_16x16x32_bf16 v[156:159], v[160:163], v[48:51], v[156:159]
	s_waitcnt vmcnt(9)
	v_mfma_f32_16x16x32_bf16 v[160:163], v[152:155], v[20:23], 0
	s_waitcnt vmcnt(8)
	v_mfma_f32_16x16x32_bf16 v[176:179], v[148:151], v[24:27], v[160:163]
	v_mfma_f32_16x16x32_bf16 v[160:163], v[152:155], v[28:31], 0
	v_mfma_f32_16x16x32_bf16 v[164:167], v[152:155], v[36:39], 0
	v_mfma_f32_16x16x32_bf16 v[152:155], v[152:155], v[44:47], 0
	v_mfma_f32_16x16x32_bf16 v[160:163], v[148:151], v[32:35], v[160:163]
	v_mfma_f32_16x16x32_bf16 v[164:167], v[148:151], v[40:43], v[164:167]
	v_mfma_f32_16x16x32_bf16 v[152:155], v[148:151], v[48:51], v[152:155]
	s_cbranch_vccnz .LBB0_163
	v_add_u32_e32 v148, 80, v207
	v_cmp_gt_u32_e64 s[6:7], s93, v148
	v_add_u32_e32 v148, 81, v207
	v_cmp_gt_u32_e64 s[8:9], s93, v148
	v_add_u32_e32 v148, 82, v207
	v_cmp_gt_u32_e64 s[10:11], s93, v148
	v_add_u32_e32 v148, 83, v207
	v_cmp_gt_u32_e64 s[12:13], s93, v148
	s_nop 1
	v_cndmask_b32_e64 v180, v180, v227, s[6:7]
	v_cndmask_b32_e64 v181, v181, v227, s[8:9]
	v_cndmask_b32_e64 v182, v182, v227, s[10:11]
	v_cndmask_b32_e64 v183, v183, v227, s[12:13]
	v_add_u32_e32 v148, 64, v207
	v_cmp_gt_u32_e64 s[6:7], s93, v148
	v_add_u32_e32 v148, 65, v207
	v_cmp_gt_u32_e64 s[8:9], s93, v148
	v_add_u32_e32 v148, 66, v207
	v_cmp_gt_u32_e64 s[10:11], s93, v148
	v_add_u32_e32 v148, 67, v207
	v_cmp_gt_u32_e64 s[12:13], s93, v148
	s_nop 1
	v_cndmask_b32_e64 v172, v172, v227, s[6:7]
	v_cndmask_b32_e64 v173, v173, v227, s[8:9]
	v_cndmask_b32_e64 v174, v174, v227, s[10:11]
	v_cndmask_b32_e64 v175, v175, v227, s[12:13]
	v_add_u32_e32 v148, 48, v207
	v_cmp_gt_u32_e64 s[6:7], s93, v148
	v_add_u32_e32 v148, 49, v207
	v_cmp_gt_u32_e64 s[8:9], s93, v148
	v_add_u32_e32 v148, 50, v207
	v_cmp_gt_u32_e64 s[10:11], s93, v148
	v_add_u32_e32 v148, 51, v207
	v_cmp_gt_u32_e64 s[12:13], s93, v148
	s_nop 1
	v_cndmask_b32_e64 v168, v168, v227, s[6:7]
	v_cndmask_b32_e64 v169, v169, v227, s[8:9]
	v_cndmask_b32_e64 v170, v170, v227, s[10:11]
	v_cndmask_b32_e64 v171, v171, v227, s[12:13]
	v_add_u32_e32 v148, 32, v207
	v_cmp_gt_u32_e64 s[6:7], s93, v148
	v_add_u32_e32 v148, 33, v207
	v_cmp_gt_u32_e64 s[8:9], s93, v148
	v_add_u32_e32 v148, 34, v207
	v_cmp_gt_u32_e64 s[10:11], s93, v148
	v_add_u32_e32 v148, 35, v207
	v_cmp_gt_u32_e64 s[12:13], s93, v148
	s_nop 1
	v_cndmask_b32_e64 v156, v156, v227, s[6:7]
	v_cndmask_b32_e64 v157, v157, v227, s[8:9]
	v_cndmask_b32_e64 v158, v158, v227, s[10:11]
	v_cndmask_b32_e64 v159, v159, v227, s[12:13]
	v_add_u32_e32 v148, 84, v207
	v_cmp_gt_u32_e64 s[6:7], s93, v148
	v_add_u32_e32 v148, 85, v207
	v_cmp_gt_u32_e64 s[8:9], s93, v148
	v_add_u32_e32 v148, 86, v207
	v_cmp_gt_u32_e64 s[10:11], s93, v148
	v_add_u32_e32 v148, 87, v207
	v_cmp_gt_u32_e64 s[12:13], s93, v148
	s_nop 1
	v_cndmask_b32_e64 v176, v176, v227, s[6:7]
	v_cndmask_b32_e64 v177, v177, v227, s[8:9]
	v_cndmask_b32_e64 v178, v178, v227, s[10:11]
	v_cndmask_b32_e64 v179, v179, v227, s[12:13]
	v_add_u32_e32 v148, 68, v207
	v_cmp_gt_u32_e64 s[6:7], s93, v148
	v_add_u32_e32 v148, 69, v207
	v_cmp_gt_u32_e64 s[8:9], s93, v148
	v_add_u32_e32 v148, 70, v207
	v_cmp_gt_u32_e64 s[10:11], s93, v148
	v_add_u32_e32 v148, 71, v207
	v_cmp_gt_u32_e64 s[12:13], s93, v148
	s_nop 1
	v_cndmask_b32_e64 v160, v160, v227, s[6:7]
	v_cndmask_b32_e64 v161, v161, v227, s[8:9]
	v_cndmask_b32_e64 v162, v162, v227, s[10:11]
	v_cndmask_b32_e64 v163, v163, v227, s[12:13]
	v_add_u32_e32 v148, 52, v207
	v_cmp_gt_u32_e64 s[6:7], s93, v148
	v_add_u32_e32 v148, 53, v207
	v_cmp_gt_u32_e64 s[8:9], s93, v148
	v_add_u32_e32 v148, 54, v207
	v_cmp_gt_u32_e64 s[10:11], s93, v148
	v_add_u32_e32 v148, 55, v207
	v_cmp_gt_u32_e64 s[12:13], s93, v148
	s_nop 1
	v_cndmask_b32_e64 v164, v164, v227, s[6:7]
	v_cndmask_b32_e64 v165, v165, v227, s[8:9]
	v_cndmask_b32_e64 v166, v166, v227, s[10:11]
	v_cndmask_b32_e64 v167, v167, v227, s[12:13]
	v_add_u32_e32 v148, 36, v207
	v_cmp_gt_u32_e64 s[6:7], s93, v148
	v_add_u32_e32 v148, 37, v207
	v_cmp_gt_u32_e64 s[8:9], s93, v148
	v_add_u32_e32 v148, 38, v207
	v_cmp_gt_u32_e64 s[10:11], s93, v148
	v_add_u32_e32 v148, 39, v207
	v_cmp_gt_u32_e64 s[12:13], s93, v148
	s_nop 1
	v_cndmask_b32_e64 v152, v152, v227, s[6:7]
	v_cndmask_b32_e64 v153, v153, v227, s[8:9]
	v_cndmask_b32_e64 v154, v154, v227, s[10:11]
	v_cndmask_b32_e64 v155, v155, v227, s[12:13]

; __device__ __forceinline__ int bid_opaque() { int b = blockIdx.x; asm volatile("" : "+s"(b)); return b; }
; __device__ void phase_mixers(const Params& p, int l, int hs, LAS unsigned char* lds, bool skip_ctx) {
;     ...
;     __builtin_amdgcn_sched_barrier(0);
;     ...
;     { const int G = (int)gridDim.x; int n3 = n_attn - 2 * G; n3 = n3 < 0 ? 0 : n3 % G;
;       for (int it = (bid_opaque() - n3 + G) % G; it < n_gmlp; it += G) gmlp_conv_item(p, l, hs, it, lds); }
.LBB0_167:
	s_waitcnt vmcnt(0) lgkmcnt(0)
	s_barrier
	s_load_dword s0, s[94:95], 0x10
	s_waitcnt lgkmcnt(0)
	s_lshr_b32 s0, s0, 16
	s_cmp_lg_u32 s0, 0
	s_cselect_b64 s[0:1], -1, 0
	s_cmp_lg_u64 s[0:1], 0
	s_addc_u32 s4, s4, 0
	s_lshl_b32 s0, s4, 1
	s_sub_i32 s5, s39, s0
	s_cmp_gt_i32 s5, -1
	s_mov_b64 s[0:1], -1
	s_cbranch_scc0 .LBB0_169
	s_abs_i32 s6, s4
	v_cvt_f32_u32_e32 v0, s6
	s_ashr_i32 s0, s5, 31
	s_abs_i32 s1, s5
	s_sub_i32 s5, 0, s6
	v_rcp_iflag_f32_e32 v0, v0
	s_nop 0
	v_mul_f32_e32 v0, 0x4f7ffffe, v0
	v_cvt_u32_f32_e32 v0, v0
	s_nop 0
	v_readfirstlane_b32 s7, v0
	s_mul_i32 s5, s5, s7
	s_mul_hi_u32 s5, s7, s5
	s_add_i32 s7, s7, s5
	s_mul_hi_u32 s5, s1, s7
	s_mul_i32 s5, s5, s6
	s_sub_i32 s1, s1, s5
	s_sub_i32 s5, s1, s6
	s_cmp_ge_u32 s1, s6
	s_cselect_b32 s1, s5, s1
	s_sub_i32 s5, s1, s6
	s_cmp_ge_u32 s1, s6
	s_cselect_b32 s1, s5, s1
	s_xor_b32 s1, s1, s0
	s_sub_i32 s8, s1, s0
	s_mov_b64 s[0:1], 0

; __device__ __forceinline__ void gmlp_conv_item(const Params& p, int l, int hs, int chunk, LAS unsigned char* lds) {
;     ...
;     { const float* cw = p.in[I_CONVW] + (size_t)l * 3 * 256;
;       const bool lat = v0 < latN;
; #pragma unroll 2
;       for (int i = 0; i < 8; ++i) {
;           const int id = i * 512 + tid, pt = id >> 5, cc = (id & 31) * 8, v = v0 + pt;
;           const int pos = lat ? (v & (SEQ - 1)) : ((v - latN) & (CTXL - 1)), n = lat ? SEQ : CTXL;
;           const bf16_t* rp = P + (size_t)v * PROJ + cc;
;           float bv[8], c1[8], h1[8], acc[8];
;           unpack8(*(const u32x4*)(rp + OFF_CB), bv); unpack8(*(const u32x4*)(rp + OFF_CC), c1); unpack8(*(const u32x4*)(rp + OFF_CH), h1);
;           { const f32x4 wa = *(const f32x4*)(cw + 256 + cc), wb = *(const f32x4*)(cw + 256 + cc + 4);
; #pragma unroll
;             for (int e = 0; e < 8; ++e) acc[e] = c1[e] * h1[e] * (e < 4 ? wa[e & 3] : wb[e & 3]); }
;           if (pos > 0) { float c0[8], h0[8]; unpack8(*(const u32x4*)(rp - PROJ + OFF_CC), c0); unpack8(*(const u32x4*)(rp - PROJ + OFF_CH), h0);
;               const f32x4 wa = *(const f32x4*)(cw + cc), wb = *(const f32x4*)(cw + cc + 4);
; #pragma unroll
;               for (int e = 0; e < 8; ++e) acc[e] += c0[e] * h0[e] * (e < 4 ? wa[e & 3] : wb[e & 3]); }
;           if (pos < n - 1) { float c2[8], h2[8]; unpack8(*(const u32x4*)(rp + PROJ + OFF_CC), c2); unpack8(*(const u32x4*)(rp + PROJ + OFF_CH), h2);
;               const f32x4 wa = *(const f32x4*)(cw + 512 + cc), wb = *(const f32x4*)(cw + 512 + cc + 4);
; #pragma unroll
;               for (int e = 0; e < 8; ++e) acc[e] += c2[e] * h2[e] * (e < 4 ? wa[e & 3] : wb[e & 3]); }
.LBB0_174:
	v_mov_b32_e32 v88, v218
	s_lshl_b32 s20, s14, 7
	v_lshlrev_b32_e32 v0, 3, v88
	s_waitcnt vmcnt(0)
	v_and_b32_e32 v2, 0xf8, v0
	s_cmp_lt_i32 s20, s15
	s_movk_i32 s0, 0x7ff
	v_lshlrev_b32_e32 v0, 1, v2
	v_lshlrev_b32_e32 v2, 2, v2
	v_mov_b32_e32 v3, v1
	s_cselect_b32 s21, s0, 0xff
	v_lshl_add_u64 v[6:7], s[52:53], 0, v[0:1]
	v_lshl_add_u64 v[8:9], s[8:9], 0, v[2:3]
	v_lshl_add_u64 v[10:11], s[6:7], 0, v[0:1]
	v_lshrrev_b32_e32 v176, 5, v88
	v_mov_b32_e32 v175, 0
	global_load_dwordx4 v[12:15], v[8:9], off
	global_load_dwordx4 v[16:19], v[8:9], off offset:16
	global_load_dwordx4 v[20:23], v[8:9], off offset:1024
	global_load_dwordx4 v[24:27], v[8:9], off offset:1040
	global_load_dwordx4 v[28:31], v[8:9], off offset:2048
	global_load_dwordx4 v[32:35], v[8:9], off offset:2064
	v_add_u32_e32 v178, 0, v176
	v_add_u32_e32 v178, s20, v178
	v_mad_i64_i32 v[180:181], s[0:1], v178, s97, v[6:7]
	v_and_b32_e32 v179, s21, v178
	v_mov_b64_e32 v[48:49], 0
	v_mov_b64_e32 v[50:51], 0
	v_mov_b64_e32 v[52:53], 0
	v_mov_b64_e32 v[54:55], 0
	v_mov_b64_e32 v[56:57], 0
	v_mov_b64_e32 v[58:59], 0
	v_mov_b64_e32 v[60:61], 0
	v_mov_b64_e32 v[62:63], 0
	v_add_co_u32_e32 v182, vcc, 0xffffe000, v180
	s_nop 1
	v_addc_co_u32_e32 v183, vcc, -1, v181, vcc
	v_add_co_u32_e32 v184, vcc, 0x2000, v180
	s_nop 1
	v_addc_co_u32_e32 v185, vcc, 0, v181, vcc
	global_load_dwordx4 v[36:39], v[180:181], off
	global_load_dwordx4 v[40:43], v[180:181], off offset:512
	global_load_dwordx4 v[44:47], v[180:181], off offset:1024
	v_cmp_ne_u32_e32 vcc, 0, v179
	s_and_saveexec_b64 s[0:1], vcc
	global_load_dwordx4 v[48:51], v[182:183], off offset:-1536
	global_load_dwordx4 v[52:55], v[182:183], off offset:-1024
	s_or_b64 exec, exec, s[0:1]
	v_cmp_ne_u32_e32 vcc, s21, v179
	s_and_saveexec_b64 s[0:1], vcc
	global_load_dwordx4 v[56:59], v[184:185], off offset:2560
	global_load_dwordx4 v[60:63], v[184:185], off offset:3072
	s_or_b64 exec, exec, s[0:1]
	v_add_u32_e32 v188, 16, v176
	v_add_u32_e32 v188, s20, v188
	v_mad_i64_i32 v[190:191], s[0:1], v188, s97, v[6:7]
	v_and_b32_e32 v189, s21, v188
	v_mov_b64_e32 v[102:103], 0
	v_mov_b64_e32 v[104:105], 0
	v_mov_b64_e32 v[106:107], 0
	v_mov_b64_e32 v[108:109], 0
	v_mov_b64_e32 v[110:111], 0
	v_mov_b64_e32 v[112:113], 0
	v_mov_b64_e32 v[114:115], 0
	v_mov_b64_e32 v[116:117], 0
	v_add_co_u32_e32 v192, vcc, 0xffffe000, v190
	s_nop 1
	v_addc_co_u32_e32 v193, vcc, -1, v191, vcc
	v_add_co_u32_e32 v194, vcc, 0x2000, v190
	s_nop 1
	v_addc_co_u32_e32 v195, vcc, 0, v191, vcc
	global_load_dwordx4 v[90:93], v[190:191], off
	global_load_dwordx4 v[94:97], v[190:191], off offset:512
	global_load_dwordx4 v[98:101], v[190:191], off offset:1024
	v_cmp_ne_u32_e32 vcc, 0, v189
	s_and_saveexec_b64 s[0:1], vcc
	global_load_dwordx4 v[102:105], v[192:193], off offset:-1536
	global_load_dwordx4 v[106:109], v[192:193], off offset:-1024
	s_or_b64 exec, exec, s[0:1]
	v_cmp_ne_u32_e32 vcc, s21, v189
	s_and_saveexec_b64 s[0:1], vcc
	global_load_dwordx4 v[110:113], v[194:195], off offset:2560
	global_load_dwordx4 v[114:117], v[194:195], off offset:3072
	s_or_b64 exec, exec, s[0:1]
	v_add_u32_e32 v198, 32, v176
	v_add_u32_e32 v198, s20, v198
	v_mad_i64_i32 v[200:201], s[0:1], v198, s97, v[6:7]
	v_and_b32_e32 v199, s21, v198
	v_mov_b64_e32 v[130:131], 0
	v_mov_b64_e32 v[132:133], 0
	v_mov_b64_e32 v[134:135], 0
	v_mov_b64_e32 v[136:137], 0
	v_mov_b64_e32 v[138:139], 0
	v_mov_b64_e32 v[140:141], 0
	v_mov_b64_e32 v[142:143], 0
	v_mov_b64_e32 v[144:145], 0
	v_add_co_u32_e32 v202, vcc, 0xffffe000, v200
	s_nop 1
	v_addc_co_u32_e32 v203, vcc, -1, v201, vcc
	v_add_co_u32_e32 v204, vcc, 0x2000, v200
	s_nop 1
	v_addc_co_u32_e32 v205, vcc, 0, v201, vcc
	global_load_dwordx4 v[118:121], v[200:201], off
	global_load_dwordx4 v[122:125], v[200:201], off offset:512
	global_load_dwordx4 v[126:129], v[200:201], off offset:1024
	v_cmp_ne_u32_e32 vcc, 0, v199
	s_and_saveexec_b64 s[0:1], vcc
	global_load_dwordx4 v[130:133], v[202:203], off offset:-1536
	global_load_dwordx4 v[134:137], v[202:203], off offset:-1024
	s_or_b64 exec, exec, s[0:1]
	v_cmp_ne_u32_e32 vcc, s21, v199
	s_and_saveexec_b64 s[0:1], vcc
	global_load_dwordx4 v[138:141], v[204:205], off offset:2560
	global_load_dwordx4 v[142:145], v[204:205], off offset:3072
	s_or_b64 exec, exec, s[0:1]
	v_add_u32_e32 v208, 48, v176
	v_add_u32_e32 v208, s20, v208
	v_mad_i64_i32 v[210:211], s[0:1], v208, s97, v[6:7]
	v_and_b32_e32 v209, s21, v208
	v_mov_b64_e32 v[158:159], 0
	v_mov_b64_e32 v[160:161], 0
	v_mov_b64_e32 v[162:163], 0
	v_mov_b64_e32 v[164:165], 0
	v_mov_b64_e32 v[166:167], 0
	v_mov_b64_e32 v[168:169], 0
	v_mov_b64_e32 v[170:171], 0
	v_mov_b64_e32 v[172:173], 0
	v_add_co_u32_e32 v212, vcc, 0xffffe000, v210
	s_nop 1
	v_addc_co_u32_e32 v213, vcc, -1, v211, vcc
	v_add_co_u32_e32 v214, vcc, 0x2000, v210
	s_nop 1
	v_addc_co_u32_e32 v215, vcc, 0, v211, vcc
	global_load_dwordx4 v[146:149], v[210:211], off
	global_load_dwordx4 v[150:153], v[210:211], off offset:512
	global_load_dwordx4 v[154:157], v[210:211], off offset:1024
	v_cmp_ne_u32_e32 vcc, 0, v209
	s_and_saveexec_b64 s[0:1], vcc
	global_load_dwordx4 v[158:161], v[212:213], off offset:-1536
	global_load_dwordx4 v[162:165], v[212:213], off offset:-1024
	s_or_b64 exec, exec, s[0:1]
	v_cmp_ne_u32_e32 vcc, s21, v209
	s_and_saveexec_b64 s[0:1], vcc
	global_load_dwordx4 v[166:169], v[214:215], off offset:2560
	global_load_dwordx4 v[170:173], v[214:215], off offset:3072
	s_or_b64 exec, exec, s[0:1]
	s_waitcnt vmcnt(21)
; __device__ __forceinline__ void gmlp_conv_item(const Params& p, int l, int hs, int chunk, LAS unsigned char* lds) {
;     ...
;           unpack8(*(const u32x4*)(rp + OFF_CB), bv); unpack8(*(const u32x4*)(rp + OFF_CC), c1); unpack8(*(const u32x4*)(rp + OFF_CH), h1);
;           { const f32x4 wa = *(const f32x4*)(cw + 256 + cc), wb = *(const f32x4*)(cw + 256 + cc + 4);
; #pragma unroll
;             for (int e = 0; e < 8; ++e) acc[e] = c1[e] * h1[e] * (e < 4 ? wa[e & 3] : wb[e & 3]); }
;           if (pos > 0) { float c0[8], h0[8]; unpack8(*(const u32x4*)(rp - PROJ + OFF_CC), c0); unpack8(*(const u32x4*)(rp - PROJ + OFF_CH), h0);
;               const f32x4 wa = *(const f32x4*)(cw + cc), wb = *(const f32x4*)(cw + cc + 4);
; #pragma unroll
;               for (int e = 0; e < 8; ++e) acc[e] += c0[e] * h0[e] * (e < 4 ? wa[e & 3] : wb[e & 3]); }
;           if (pos < n - 1) { float c2[8], h2[8]; unpack8(*(const u32x4*)(rp + PROJ + OFF_CC), c2); unpack8(*(const u32x4*)(rp + PROJ + OFF_CH), h2);
;               const f32x4 wa = *(const f32x4*)(cw + 512 + cc), wb = *(const f32x4*)(cw + 512 + cc + 4);
; #pragma unroll
;               for (int e = 0; e < 8; ++e) acc[e] += c2[e] * h2[e] * (e < 4 ? wa[e & 3] : wb[e & 3]); }
; #pragma unroll
;           for (int e = 0; e < 8; ++e) acc[e] *= bv[e];
;           *(u32x4*)(Y + (size_t)v * D + cc) = pack8(acc);
	v_lshlrev_b32_e32 v72, 16, v40
	v_and_b32_e32 v73, 0xffff0000, v40
	v_lshlrev_b32_e32 v80, 16, v44
	v_and_b32_e32 v81, 0xffff0000, v44
	v_lshlrev_b32_e32 v74, 16, v41
	v_and_b32_e32 v75, 0xffff0000, v41
	v_lshlrev_b32_e32 v82, 16, v45
	v_and_b32_e32 v83, 0xffff0000, v45
	v_lshlrev_b32_e32 v76, 16, v42
	v_and_b32_e32 v77, 0xffff0000, v42
	v_lshlrev_b32_e32 v84, 16, v46
	v_and_b32_e32 v85, 0xffff0000, v46
	v_lshlrev_b32_e32 v78, 16, v43
	v_and_b32_e32 v79, 0xffff0000, v43
	v_lshlrev_b32_e32 v86, 16, v47
	v_and_b32_e32 v87, 0xffff0000, v47
	v_pk_mul_f32 v[64:65], v[72:73], v[80:81]
	v_pk_mul_f32 v[66:67], v[74:75], v[82:83]
	v_pk_mul_f32 v[68:69], v[76:77], v[84:85]
	v_pk_mul_f32 v[70:71], v[78:79], v[86:87]
	v_pk_mul_f32 v[64:65], v[20:21], v[64:65]
	v_pk_mul_f32 v[66:67], v[22:23], v[66:67]
	v_pk_mul_f32 v[68:69], v[24:25], v[68:69]
	v_pk_mul_f32 v[70:71], v[26:27], v[70:71]
	v_lshlrev_b32_e32 v72, 16, v48
	v_and_b32_e32 v73, 0xffff0000, v48
	v_lshlrev_b32_e32 v80, 16, v52
	v_and_b32_e32 v81, 0xffff0000, v52
	v_lshlrev_b32_e32 v74, 16, v49
	v_and_b32_e32 v75, 0xffff0000, v49
	v_lshlrev_b32_e32 v82, 16, v53
	v_and_b32_e32 v83, 0xffff0000, v53
	v_lshlrev_b32_e32 v76, 16, v50
	v_and_b32_e32 v77, 0xffff0000, v50
	v_lshlrev_b32_e32 v84, 16, v54
	v_and_b32_e32 v85, 0xffff0000, v54
	v_lshlrev_b32_e32 v78, 16, v51
	v_and_b32_e32 v79, 0xffff0000, v51
	v_lshlrev_b32_e32 v86, 16, v55
	v_and_b32_e32 v87, 0xffff0000, v55
	v_pk_mul_f32 v[72:73], v[72:73], v[80:81]
	v_pk_mul_f32 v[74:75], v[74:75], v[82:83]
	v_pk_mul_f32 v[76:77], v[76:77], v[84:85]
	v_pk_mul_f32 v[78:79], v[78:79], v[86:87]
	v_pk_fma_f32 v[64:65], v[12:13], v[72:73], v[64:65]
	v_pk_fma_f32 v[66:67], v[14:15], v[74:75], v[66:67]
	v_pk_fma_f32 v[68:69], v[16:17], v[76:77], v[68:69]
	v_pk_fma_f32 v[70:71], v[18:19], v[78:79], v[70:71]
	v_lshlrev_b32_e32 v72, 16, v56
	v_and_b32_e32 v73, 0xffff0000, v56
	v_lshlrev_b32_e32 v80, 16, v60
	v_and_b32_e32 v81, 0xffff0000, v60
	v_lshlrev_b32_e32 v74, 16, v57
	v_and_b32_e32 v75, 0xffff0000, v57
	v_lshlrev_b32_e32 v82, 16, v61
	v_and_b32_e32 v83, 0xffff0000, v61
	v_lshlrev_b32_e32 v76, 16, v58
	v_and_b32_e32 v77, 0xffff0000, v58
	v_lshlrev_b32_e32 v84, 16, v62
	v_and_b32_e32 v85, 0xffff0000, v62
	v_lshlrev_b32_e32 v78, 16, v59
	v_and_b32_e32 v79, 0xffff0000, v59
	v_lshlrev_b32_e32 v86, 16, v63
	v_and_b32_e32 v87, 0xffff0000, v63
	v_pk_mul_f32 v[72:73], v[72:73], v[80:81]
	v_pk_mul_f32 v[74:75], v[74:75], v[82:83]
	v_pk_mul_f32 v[76:77], v[76:77], v[84:85]
	v_pk_mul_f32 v[78:79], v[78:79], v[86:87]
	v_pk_fma_f32 v[64:65], v[28:29], v[72:73], v[64:65]
	v_pk_fma_f32 v[66:67], v[30:31], v[74:75], v[66:67]
	v_pk_fma_f32 v[68:69], v[32:33], v[76:77], v[68:69]
	v_pk_fma_f32 v[70:71], v[34:35], v[78:79], v[70:71]
	v_lshlrev_b32_e32 v72, 16, v36
	v_and_b32_e32 v73, 0xffff0000, v36
	v_lshlrev_b32_e32 v74, 16, v37
	v_and_b32_e32 v75, 0xffff0000, v37
	v_lshlrev_b32_e32 v76, 16, v38
	v_and_b32_e32 v77, 0xffff0000, v38
	v_lshlrev_b32_e32 v78, 16, v39
	v_and_b32_e32 v79, 0xffff0000, v39
	v_mul_f32_e32 v64, v64, v72
	v_mul_f32_e32 v65, v65, v73
	v_mul_f32_e32 v66, v66, v74
	v_mul_f32_e32 v67, v67, v75
	v_mul_f32_e32 v68, v68, v76
	v_mul_f32_e32 v69, v69, v77
	v_mul_f32_e32 v70, v70, v78
	v_mul_f32_e32 v71, v71, v79
	v_cvt_pk_bf16_f32 v2, v64, v65
	v_cvt_pk_bf16_f32 v3, v66, v67
	v_cvt_pk_bf16_f32 v4, v68, v69
	v_cvt_pk_bf16_f32 v5, v70, v71
	v_lshlrev_b32_e32 v174, 11, v178
	v_lshl_add_u64 v[186:187], v[10:11], 0, v[174:175]
	global_store_dwordx4 v[186:187], v[2:5], off
	v_add_u32_e32 v178, 64, v176
	v_add_u32_e32 v178, s20, v178
	v_mad_i64_i32 v[180:181], s[0:1], v178, s97, v[6:7]
	v_and_b32_e32 v179, s21, v178
	v_mov_b64_e32 v[48:49], 0
	v_mov_b64_e32 v[50:51], 0
	v_mov_b64_e32 v[52:53], 0
	v_mov_b64_e32 v[54:55], 0
	v_mov_b64_e32 v[56:57], 0
	v_mov_b64_e32 v[58:59], 0
	v_mov_b64_e32 v[60:61], 0
	v_mov_b64_e32 v[62:63], 0
	v_add_co_u32_e32 v182, vcc, 0xffffe000, v180
	s_nop 1
	v_addc_co_u32_e32 v183, vcc, -1, v181, vcc
	v_add_co_u32_e32 v184, vcc, 0x2000, v180
	s_nop 1
	v_addc_co_u32_e32 v185, vcc, 0, v181, vcc
	global_load_dwordx4 v[36:39], v[180:181], off
	global_load_dwordx4 v[40:43], v[180:181], off offset:512
	global_load_dwordx4 v[44:47], v[180:181], off offset:1024
	v_cmp_ne_u32_e32 vcc, 0, v179
	s_and_saveexec_b64 s[0:1], vcc
	global_load_dwordx4 v[48:51], v[182:183], off offset:-1536
	global_load_dwordx4 v[52:55], v[182:183], off offset:-1024
	s_or_b64 exec, exec, s[0:1]
	v_cmp_ne_u32_e32 vcc, s21, v179
	s_and_saveexec_b64 s[0:1], vcc
	global_load_dwordx4 v[56:59], v[184:185], off offset:2560
	global_load_dwordx4 v[60:63], v[184:185], off offset:3072
	s_or_b64 exec, exec, s[0:1]
	s_waitcnt vmcnt(22)
; __device__ __forceinline__ void gmlp_conv_item(const Params& p, int l, int hs, int chunk, LAS unsigned char* lds) {
;     ...
;           unpack8(*(const u32x4*)(rp + OFF_CB), bv); unpack8(*(const u32x4*)(rp + OFF_CC), c1); unpack8(*(const u32x4*)(rp + OFF_CH), h1);
;           { const f32x4 wa = *(const f32x4*)(cw + 256 + cc), wb = *(const f32x4*)(cw + 256 + cc + 4);
; #pragma unroll
;             for (int e = 0; e < 8; ++e) acc[e] = c1[e] * h1[e] * (e < 4 ? wa[e & 3] : wb[e & 3]); }
;           if (pos > 0) { float c0[8], h0[8]; unpack8(*(const u32x4*)(rp - PROJ + OFF_CC), c0); unpack8(*(const u32x4*)(rp - PROJ + OFF_CH), h0);
;               const f32x4 wa = *(const f32x4*)(cw + cc), wb = *(const f32x4*)(cw + cc + 4);
; #pragma unroll
;               for (int e = 0; e < 8; ++e) acc[e] += c0[e] * h0[e] * (e < 4 ? wa[e & 3] : wb[e & 3]); }
;           if (pos < n - 1) { float c2[8], h2[8]; unpack8(*(const u32x4*)(rp + PROJ + OFF_CC), c2); unpack8(*(const u32x4*)(rp + PROJ + OFF_CH), h2);
;               const f32x4 wa = *(const f32x4*)(cw + 512 + cc), wb = *(const f32x4*)(cw + 512 + cc + 4);
; #pragma unroll
;               for (int e = 0; e < 8; ++e) acc[e] += c2[e] * h2[e] * (e < 4 ? wa[e & 3] : wb[e & 3]); }
; #pragma unroll
;           for (int e = 0; e < 8; ++e) acc[e] *= bv[e];
;           *(u32x4*)(Y + (size_t)v * D + cc) = pack8(acc);
	v_lshlrev_b32_e32 v72, 16, v94
	v_and_b32_e32 v73, 0xffff0000, v94
	v_lshlrev_b32_e32 v80, 16, v98
	v_and_b32_e32 v81, 0xffff0000, v98
	v_lshlrev_b32_e32 v74, 16, v95
	v_and_b32_e32 v75, 0xffff0000, v95
	v_lshlrev_b32_e32 v82, 16, v99
	v_and_b32_e32 v83, 0xffff0000, v99
	v_lshlrev_b32_e32 v76, 16, v96
	v_and_b32_e32 v77, 0xffff0000, v96
	v_lshlrev_b32_e32 v84, 16, v100
	v_and_b32_e32 v85, 0xffff0000, v100
	v_lshlrev_b32_e32 v78, 16, v97
	v_and_b32_e32 v79, 0xffff0000, v97
	v_lshlrev_b32_e32 v86, 16, v101
	v_and_b32_e32 v87, 0xffff0000, v101
	v_pk_mul_f32 v[64:65], v[72:73], v[80:81]
	v_pk_mul_f32 v[66:67], v[74:75], v[82:83]
	v_pk_mul_f32 v[68:69], v[76:77], v[84:85]
	v_pk_mul_f32 v[70:71], v[78:79], v[86:87]
	v_pk_mul_f32 v[64:65], v[20:21], v[64:65]
	v_pk_mul_f32 v[66:67], v[22:23], v[66:67]
	v_pk_mul_f32 v[68:69], v[24:25], v[68:69]
	v_pk_mul_f32 v[70:71], v[26:27], v[70:71]
	v_lshlrev_b32_e32 v72, 16, v102
	v_and_b32_e32 v73, 0xffff0000, v102
	v_lshlrev_b32_e32 v80, 16, v106
	v_and_b32_e32 v81, 0xffff0000, v106
	v_lshlrev_b32_e32 v74, 16, v103
	v_and_b32_e32 v75, 0xffff0000, v103
	v_lshlrev_b32_e32 v82, 16, v107
	v_and_b32_e32 v83, 0xffff0000, v107
	v_lshlrev_b32_e32 v76, 16, v104
	v_and_b32_e32 v77, 0xffff0000, v104
	v_lshlrev_b32_e32 v84, 16, v108
	v_and_b32_e32 v85, 0xffff0000, v108
	v_lshlrev_b32_e32 v78, 16, v105
	v_and_b32_e32 v79, 0xffff0000, v105
	v_lshlrev_b32_e32 v86, 16, v109
	v_and_b32_e32 v87, 0xffff0000, v109
	v_pk_mul_f32 v[72:73], v[72:73], v[80:81]
	v_pk_mul_f32 v[74:75], v[74:75], v[82:83]
	v_pk_mul_f32 v[76:77], v[76:77], v[84:85]
	v_pk_mul_f32 v[78:79], v[78:79], v[86:87]
	v_pk_fma_f32 v[64:65], v[12:13], v[72:73], v[64:65]
	v_pk_fma_f32 v[66:67], v[14:15], v[74:75], v[66:67]
	v_pk_fma_f32 v[68:69], v[16:17], v[76:77], v[68:69]
	v_pk_fma_f32 v[70:71], v[18:19], v[78:79], v[70:71]
	v_lshlrev_b32_e32 v72, 16, v110
	v_and_b32_e32 v73, 0xffff0000, v110
	v_lshlrev_b32_e32 v80, 16, v114
	v_and_b32_e32 v81, 0xffff0000, v114
	v_lshlrev_b32_e32 v74, 16, v111
	v_and_b32_e32 v75, 0xffff0000, v111
	v_lshlrev_b32_e32 v82, 16, v115
	v_and_b32_e32 v83, 0xffff0000, v115
	v_lshlrev_b32_e32 v76, 16, v112
	v_and_b32_e32 v77, 0xffff0000, v112
	v_lshlrev_b32_e32 v84, 16, v116
	v_and_b32_e32 v85, 0xffff0000, v116
	v_lshlrev_b32_e32 v78, 16, v113
	v_and_b32_e32 v79, 0xffff0000, v113
	v_lshlrev_b32_e32 v86, 16, v117
	v_and_b32_e32 v87, 0xffff0000, v117
	v_pk_mul_f32 v[72:73], v[72:73], v[80:81]
	v_pk_mul_f32 v[74:75], v[74:75], v[82:83]
	v_pk_mul_f32 v[76:77], v[76:77], v[84:85]
	v_pk_mul_f32 v[78:79], v[78:79], v[86:87]
	v_pk_fma_f32 v[64:65], v[28:29], v[72:73], v[64:65]
	v_pk_fma_f32 v[66:67], v[30:31], v[74:75], v[66:67]
	v_pk_fma_f32 v[68:69], v[32:33], v[76:77], v[68:69]
	v_pk_fma_f32 v[70:71], v[34:35], v[78:79], v[70:71]
	v_lshlrev_b32_e32 v72, 16, v90
	v_and_b32_e32 v73, 0xffff0000, v90
	v_lshlrev_b32_e32 v74, 16, v91
	v_and_b32_e32 v75, 0xffff0000, v91
	v_lshlrev_b32_e32 v76, 16, v92
	v_and_b32_e32 v77, 0xffff0000, v92
	v_lshlrev_b32_e32 v78, 16, v93
	v_and_b32_e32 v79, 0xffff0000, v93
	v_mul_f32_e32 v64, v64, v72
	v_mul_f32_e32 v65, v65, v73
	v_mul_f32_e32 v66, v66, v74
	v_mul_f32_e32 v67, v67, v75
	v_mul_f32_e32 v68, v68, v76
	v_mul_f32_e32 v69, v69, v77
	v_mul_f32_e32 v70, v70, v78
	v_mul_f32_e32 v71, v71, v79
	v_cvt_pk_bf16_f32 v2, v64, v65
	v_cvt_pk_bf16_f32 v3, v66, v67
	v_cvt_pk_bf16_f32 v4, v68, v69
	v_cvt_pk_bf16_f32 v5, v70, v71
	v_lshlrev_b32_e32 v174, 11, v188
	v_lshl_add_u64 v[196:197], v[10:11], 0, v[174:175]
	global_store_dwordx4 v[196:197], v[2:5], off
	v_add_u32_e32 v188, 80, v176
	v_add_u32_e32 v188, s20, v188
	v_mad_i64_i32 v[190:191], s[0:1], v188, s97, v[6:7]
	v_and_b32_e32 v189, s21, v188
	v_mov_b64_e32 v[102:103], 0
	v_mov_b64_e32 v[104:105], 0
	v_mov_b64_e32 v[106:107], 0
	v_mov_b64_e32 v[108:109], 0
	v_mov_b64_e32 v[110:111], 0
	v_mov_b64_e32 v[112:113], 0
	v_mov_b64_e32 v[114:115], 0
	v_mov_b64_e32 v[116:117], 0
	v_add_co_u32_e32 v192, vcc, 0xffffe000, v190
	s_nop 1
	v_addc_co_u32_e32 v193, vcc, -1, v191, vcc
	v_add_co_u32_e32 v194, vcc, 0x2000, v190
	s_nop 1
	v_addc_co_u32_e32 v195, vcc, 0, v191, vcc
	global_load_dwordx4 v[90:93], v[190:191], off
	global_load_dwordx4 v[94:97], v[190:191], off offset:512
	global_load_dwordx4 v[98:101], v[190:191], off offset:1024
	v_cmp_ne_u32_e32 vcc, 0, v189
	s_and_saveexec_b64 s[0:1], vcc
	global_load_dwordx4 v[102:105], v[192:193], off offset:-1536
	global_load_dwordx4 v[106:109], v[192:193], off offset:-1024
	s_or_b64 exec, exec, s[0:1]
	v_cmp_ne_u32_e32 vcc, s21, v189
	s_and_saveexec_b64 s[0:1], vcc
	global_load_dwordx4 v[110:113], v[194:195], off offset:2560
	global_load_dwordx4 v[114:117], v[194:195], off offset:3072
	s_or_b64 exec, exec, s[0:1]
	s_waitcnt vmcnt(23)
; __device__ __forceinline__ void gmlp_conv_item(const Params& p, int l, int hs, int chunk, LAS unsigned char* lds) {
;     ...
;           unpack8(*(const u32x4*)(rp + OFF_CB), bv); unpack8(*(const u32x4*)(rp + OFF_CC), c1); unpack8(*(const u32x4*)(rp + OFF_CH), h1);
;           { const f32x4 wa = *(const f32x4*)(cw + 256 + cc), wb = *(const f32x4*)(cw + 256 + cc + 4);
; #pragma unroll
;             for (int e = 0; e < 8; ++e) acc[e] = c1[e] * h1[e] * (e < 4 ? wa[e & 3] : wb[e & 3]); }
;           if (pos > 0) { float c0[8], h0[8]; unpack8(*(const u32x4*)(rp - PROJ + OFF_CC), c0); unpack8(*(const u32x4*)(rp - PROJ + OFF_CH), h0);
;               const f32x4 wa = *(const f32x4*)(cw + cc), wb = *(const f32x4*)(cw + cc + 4);
; #pragma unroll
;               for (int e = 0; e < 8; ++e) acc[e] += c0[e] * h0[e] * (e < 4 ? wa[e & 3] : wb[e & 3]); }
;           if (pos < n - 1) { float c2[8], h2[8]; unpack8(*(const u32x4*)(rp + PROJ + OFF_CC), c2); unpack8(*(const u32x4*)(rp + PROJ + OFF_CH), h2);
;               const f32x4 wa = *(const f32x4*)(cw + 512 + cc), wb = *(const f32x4*)(cw + 512 + cc + 4);
; #pragma unroll
;               for (int e = 0; e < 8; ++e) acc[e] += c2[e] * h2[e] * (e < 4 ? wa[e & 3] : wb[e & 3]); }
; #pragma unroll
;           for (int e = 0; e < 8; ++e) acc[e] *= bv[e];
;           *(u32x4*)(Y + (size_t)v * D + cc) = pack8(acc);
	v_lshlrev_b32_e32 v72, 16, v122
	v_and_b32_e32 v73, 0xffff0000, v122
	v_lshlrev_b32_e32 v80, 16, v126
	v_and_b32_e32 v81, 0xffff0000, v126
	v_lshlrev_b32_e32 v74, 16, v123
	v_and_b32_e32 v75, 0xffff0000, v123
	v_lshlrev_b32_e32 v82, 16, v127
	v_and_b32_e32 v83, 0xffff0000, v127
	v_lshlrev_b32_e32 v76, 16, v124
	v_and_b32_e32 v77, 0xffff0000, v124
	v_lshlrev_b32_e32 v84, 16, v128
	v_and_b32_e32 v85, 0xffff0000, v128
	v_lshlrev_b32_e32 v78, 16, v125
	v_and_b32_e32 v79, 0xffff0000, v125
	v_lshlrev_b32_e32 v86, 16, v129
	v_and_b32_e32 v87, 0xffff0000, v129
	v_pk_mul_f32 v[64:65], v[72:73], v[80:81]
	v_pk_mul_f32 v[66:67], v[74:75], v[82:83]
	v_pk_mul_f32 v[68:69], v[76:77], v[84:85]
	v_pk_mul_f32 v[70:71], v[78:79], v[86:87]
	v_pk_mul_f32 v[64:65], v[20:21], v[64:65]
	v_pk_mul_f32 v[66:67], v[22:23], v[66:67]
	v_pk_mul_f32 v[68:69], v[24:25], v[68:69]
	v_pk_mul_f32 v[70:71], v[26:27], v[70:71]
	v_lshlrev_b32_e32 v72, 16, v130
	v_and_b32_e32 v73, 0xffff0000, v130
	v_lshlrev_b32_e32 v80, 16, v134
	v_and_b32_e32 v81, 0xffff0000, v134
	v_lshlrev_b32_e32 v74, 16, v131
	v_and_b32_e32 v75, 0xffff0000, v131
	v_lshlrev_b32_e32 v82, 16, v135
	v_and_b32_e32 v83, 0xffff0000, v135
	v_lshlrev_b32_e32 v76, 16, v132
	v_and_b32_e32 v77, 0xffff0000, v132
	v_lshlrev_b32_e32 v84, 16, v136
	v_and_b32_e32 v85, 0xffff0000, v136
	v_lshlrev_b32_e32 v78, 16, v133
	v_and_b32_e32 v79, 0xffff0000, v133
	v_lshlrev_b32_e32 v86, 16, v137
	v_and_b32_e32 v87, 0xffff0000, v137
	v_pk_mul_f32 v[72:73], v[72:73], v[80:81]
	v_pk_mul_f32 v[74:75], v[74:75], v[82:83]
	v_pk_mul_f32 v[76:77], v[76:77], v[84:85]
	v_pk_mul_f32 v[78:79], v[78:79], v[86:87]
	v_pk_fma_f32 v[64:65], v[12:13], v[72:73], v[64:65]
	v_pk_fma_f32 v[66:67], v[14:15], v[74:75], v[66:67]
	v_pk_fma_f32 v[68:69], v[16:17], v[76:77], v[68:69]
	v_pk_fma_f32 v[70:71], v[18:19], v[78:79], v[70:71]
	v_lshlrev_b32_e32 v72, 16, v138
	v_and_b32_e32 v73, 0xffff0000, v138
	v_lshlrev_b32_e32 v80, 16, v142
	v_and_b32_e32 v81, 0xffff0000, v142
	v_lshlrev_b32_e32 v74, 16, v139
	v_and_b32_e32 v75, 0xffff0000, v139
	v_lshlrev_b32_e32 v82, 16, v143
	v_and_b32_e32 v83, 0xffff0000, v143
	v_lshlrev_b32_e32 v76, 16, v140
	v_and_b32_e32 v77, 0xffff0000, v140
	v_lshlrev_b32_e32 v84, 16, v144
	v_and_b32_e32 v85, 0xffff0000, v144
	v_lshlrev_b32_e32 v78, 16, v141
	v_and_b32_e32 v79, 0xffff0000, v141
	v_lshlrev_b32_e32 v86, 16, v145
	v_and_b32_e32 v87, 0xffff0000, v145
	v_pk_mul_f32 v[72:73], v[72:73], v[80:81]
	v_pk_mul_f32 v[74:75], v[74:75], v[82:83]
	v_pk_mul_f32 v[76:77], v[76:77], v[84:85]
	v_pk_mul_f32 v[78:79], v[78:79], v[86:87]
	v_pk_fma_f32 v[64:65], v[28:29], v[72:73], v[64:65]
	v_pk_fma_f32 v[66:67], v[30:31], v[74:75], v[66:67]
	v_pk_fma_f32 v[68:69], v[32:33], v[76:77], v[68:69]
	v_pk_fma_f32 v[70:71], v[34:35], v[78:79], v[70:71]
	v_lshlrev_b32_e32 v72, 16, v118
	v_and_b32_e32 v73, 0xffff0000, v118
	v_lshlrev_b32_e32 v74, 16, v119
	v_and_b32_e32 v75, 0xffff0000, v119
	v_lshlrev_b32_e32 v76, 16, v120
	v_and_b32_e32 v77, 0xffff0000, v120
	v_lshlrev_b32_e32 v78, 16, v121
	v_and_b32_e32 v79, 0xffff0000, v121
	v_mul_f32_e32 v64, v64, v72
	v_mul_f32_e32 v65, v65, v73
	v_mul_f32_e32 v66, v66, v74
	v_mul_f32_e32 v67, v67, v75
	v_mul_f32_e32 v68, v68, v76
	v_mul_f32_e32 v69, v69, v77
	v_mul_f32_e32 v70, v70, v78
	v_mul_f32_e32 v71, v71, v79
	v_cvt_pk_bf16_f32 v2, v64, v65
	v_cvt_pk_bf16_f32 v3, v66, v67
	v_cvt_pk_bf16_f32 v4, v68, v69
	v_cvt_pk_bf16_f32 v5, v70, v71
	v_lshlrev_b32_e32 v174, 11, v198
	v_lshl_add_u64 v[206:207], v[10:11], 0, v[174:175]
	global_store_dwordx4 v[206:207], v[2:5], off
	v_add_u32_e32 v198, 96, v176
	v_add_u32_e32 v198, s20, v198
	v_mad_i64_i32 v[200:201], s[0:1], v198, s97, v[6:7]
	v_and_b32_e32 v199, s21, v198
	v_mov_b64_e32 v[130:131], 0
	v_mov_b64_e32 v[132:133], 0
	v_mov_b64_e32 v[134:135], 0
	v_mov_b64_e32 v[136:137], 0
	v_mov_b64_e32 v[138:139], 0
	v_mov_b64_e32 v[140:141], 0
	v_mov_b64_e32 v[142:143], 0
	v_mov_b64_e32 v[144:145], 0
	v_add_co_u32_e32 v202, vcc, 0xffffe000, v200
	s_nop 1
	v_addc_co_u32_e32 v203, vcc, -1, v201, vcc
	v_add_co_u32_e32 v204, vcc, 0x2000, v200
	s_nop 1
	v_addc_co_u32_e32 v205, vcc, 0, v201, vcc
	global_load_dwordx4 v[118:121], v[200:201], off
	global_load_dwordx4 v[122:125], v[200:201], off offset:512
	global_load_dwordx4 v[126:129], v[200:201], off offset:1024
	v_cmp_ne_u32_e32 vcc, 0, v199
	s_and_saveexec_b64 s[0:1], vcc
	global_load_dwordx4 v[130:133], v[202:203], off offset:-1536
	global_load_dwordx4 v[134:137], v[202:203], off offset:-1024
	s_or_b64 exec, exec, s[0:1]
	v_cmp_ne_u32_e32 vcc, s21, v199
	s_and_saveexec_b64 s[0:1], vcc
	global_load_dwordx4 v[138:141], v[204:205], off offset:2560
	global_load_dwordx4 v[142:145], v[204:205], off offset:3072
	s_or_b64 exec, exec, s[0:1]
	s_waitcnt vmcnt(24)
; __device__ __forceinline__ void gmlp_conv_item(const Params& p, int l, int hs, int chunk, LAS unsigned char* lds) {
;     ...
;           unpack8(*(const u32x4*)(rp + OFF_CB), bv); unpack8(*(const u32x4*)(rp + OFF_CC), c1); unpack8(*(const u32x4*)(rp + OFF_CH), h1);
;           { const f32x4 wa = *(const f32x4*)(cw + 256 + cc), wb = *(const f32x4*)(cw + 256 + cc + 4);
; #pragma unroll
;             for (int e = 0; e < 8; ++e) acc[e] = c1[e] * h1[e] * (e < 4 ? wa[e & 3] : wb[e & 3]); }
;           if (pos > 0) { float c0[8], h0[8]; unpack8(*(const u32x4*)(rp - PROJ + OFF_CC), c0); unpack8(*(const u32x4*)(rp - PROJ + OFF_CH), h0);
;               const f32x4 wa = *(const f32x4*)(cw + cc), wb = *(const f32x4*)(cw + cc + 4);
; #pragma unroll
;               for (int e = 0; e < 8; ++e) acc[e] += c0[e] * h0[e] * (e < 4 ? wa[e & 3] : wb[e & 3]); }
;           if (pos < n - 1) { float c2[8], h2[8]; unpack8(*(const u32x4*)(rp + PROJ + OFF_CC), c2); unpack8(*(const u32x4*)(rp + PROJ + OFF_CH), h2);
;               const f32x4 wa = *(const f32x4*)(cw + 512 + cc), wb = *(const f32x4*)(cw + 512 + cc + 4);
; #pragma unroll
;               for (int e = 0; e < 8; ++e) acc[e] += c2[e] * h2[e] * (e < 4 ? wa[e & 3] : wb[e & 3]); }
; #pragma unroll
;           for (int e = 0; e < 8; ++e) acc[e] *= bv[e];
;           *(u32x4*)(Y + (size_t)v * D + cc) = pack8(acc);
	v_lshlrev_b32_e32 v72, 16, v150
	v_and_b32_e32 v73, 0xffff0000, v150
	v_lshlrev_b32_e32 v80, 16, v154
	v_and_b32_e32 v81, 0xffff0000, v154
	v_lshlrev_b32_e32 v74, 16, v151
	v_and_b32_e32 v75, 0xffff0000, v151
	v_lshlrev_b32_e32 v82, 16, v155
	v_and_b32_e32 v83, 0xffff0000, v155
	v_lshlrev_b32_e32 v76, 16, v152
	v_and_b32_e32 v77, 0xffff0000, v152
	v_lshlrev_b32_e32 v84, 16, v156
	v_and_b32_e32 v85, 0xffff0000, v156
	v_lshlrev_b32_e32 v78, 16, v153
	v_and_b32_e32 v79, 0xffff0000, v153
	v_lshlrev_b32_e32 v86, 16, v157
	v_and_b32_e32 v87, 0xffff0000, v157
	v_pk_mul_f32 v[64:65], v[72:73], v[80:81]
	v_pk_mul_f32 v[66:67], v[74:75], v[82:83]
	v_pk_mul_f32 v[68:69], v[76:77], v[84:85]
	v_pk_mul_f32 v[70:71], v[78:79], v[86:87]
	v_pk_mul_f32 v[64:65], v[20:21], v[64:65]
	v_pk_mul_f32 v[66:67], v[22:23], v[66:67]
	v_pk_mul_f32 v[68:69], v[24:25], v[68:69]
	v_pk_mul_f32 v[70:71], v[26:27], v[70:71]
	v_lshlrev_b32_e32 v72, 16, v158
	v_and_b32_e32 v73, 0xffff0000, v158
	v_lshlrev_b32_e32 v80, 16, v162
	v_and_b32_e32 v81, 0xffff0000, v162
	v_lshlrev_b32_e32 v74, 16, v159
	v_and_b32_e32 v75, 0xffff0000, v159
	v_lshlrev_b32_e32 v82, 16, v163
	v_and_b32_e32 v83, 0xffff0000, v163
	v_lshlrev_b32_e32 v76, 16, v160
	v_and_b32_e32 v77, 0xffff0000, v160
	v_lshlrev_b32_e32 v84, 16, v164
	v_and_b32_e32 v85, 0xffff0000, v164
	v_lshlrev_b32_e32 v78, 16, v161
	v_and_b32_e32 v79, 0xffff0000, v161
	v_lshlrev_b32_e32 v86, 16, v165
	v_and_b32_e32 v87, 0xffff0000, v165
	v_pk_mul_f32 v[72:73], v[72:73], v[80:81]
	v_pk_mul_f32 v[74:75], v[74:75], v[82:83]
	v_pk_mul_f32 v[76:77], v[76:77], v[84:85]
	v_pk_mul_f32 v[78:79], v[78:79], v[86:87]
	v_pk_fma_f32 v[64:65], v[12:13], v[72:73], v[64:65]
	v_pk_fma_f32 v[66:67], v[14:15], v[74:75], v[66:67]
	v_pk_fma_f32 v[68:69], v[16:17], v[76:77], v[68:69]
	v_pk_fma_f32 v[70:71], v[18:19], v[78:79], v[70:71]
	v_lshlrev_b32_e32 v72, 16, v166
	v_and_b32_e32 v73, 0xffff0000, v166
	v_lshlrev_b32_e32 v80, 16, v170
	v_and_b32_e32 v81, 0xffff0000, v170
	v_lshlrev_b32_e32 v74, 16, v167
	v_and_b32_e32 v75, 0xffff0000, v167
	v_lshlrev_b32_e32 v82, 16, v171
	v_and_b32_e32 v83, 0xffff0000, v171
	v_lshlrev_b32_e32 v76, 16, v168
	v_and_b32_e32 v77, 0xffff0000, v168
	v_lshlrev_b32_e32 v84, 16, v172
	v_and_b32_e32 v85, 0xffff0000, v172
	v_lshlrev_b32_e32 v78, 16, v169
	v_and_b32_e32 v79, 0xffff0000, v169
	v_lshlrev_b32_e32 v86, 16, v173
	v_and_b32_e32 v87, 0xffff0000, v173
	v_pk_mul_f32 v[72:73], v[72:73], v[80:81]
	v_pk_mul_f32 v[74:75], v[74:75], v[82:83]
	v_pk_mul_f32 v[76:77], v[76:77], v[84:85]
	v_pk_mul_f32 v[78:79], v[78:79], v[86:87]
	v_pk_fma_f32 v[64:65], v[28:29], v[72:73], v[64:65]
	v_pk_fma_f32 v[66:67], v[30:31], v[74:75], v[66:67]
	v_pk_fma_f32 v[68:69], v[32:33], v[76:77], v[68:69]
	v_pk_fma_f32 v[70:71], v[34:35], v[78:79], v[70:71]
	v_lshlrev_b32_e32 v72, 16, v146
	v_and_b32_e32 v73, 0xffff0000, v146
	v_lshlrev_b32_e32 v74, 16, v147
	v_and_b32_e32 v75, 0xffff0000, v147
	v_lshlrev_b32_e32 v76, 16, v148
	v_and_b32_e32 v77, 0xffff0000, v148
	v_lshlrev_b32_e32 v78, 16, v149
	v_and_b32_e32 v79, 0xffff0000, v149
	v_mul_f32_e32 v64, v64, v72
	v_mul_f32_e32 v65, v65, v73
	v_mul_f32_e32 v66, v66, v74
	v_mul_f32_e32 v67, v67, v75
	v_mul_f32_e32 v68, v68, v76
	v_mul_f32_e32 v69, v69, v77
	v_mul_f32_e32 v70, v70, v78
	v_mul_f32_e32 v71, v71, v79
	v_cvt_pk_bf16_f32 v2, v64, v65
	v_cvt_pk_bf16_f32 v3, v66, v67
	v_cvt_pk_bf16_f32 v4, v68, v69
	v_cvt_pk_bf16_f32 v5, v70, v71
	v_lshlrev_b32_e32 v174, 11, v208
	v_lshl_add_u64 v[216:217], v[10:11], 0, v[174:175]
	global_store_dwordx4 v[216:217], v[2:5], off
	v_add_u32_e32 v208, 112, v176
	v_add_u32_e32 v208, s20, v208
	v_mad_i64_i32 v[210:211], s[0:1], v208, s97, v[6:7]
	v_and_b32_e32 v209, s21, v208
	v_mov_b64_e32 v[158:159], 0
	v_mov_b64_e32 v[160:161], 0
	v_mov_b64_e32 v[162:163], 0
	v_mov_b64_e32 v[164:165], 0
	v_mov_b64_e32 v[166:167], 0
	v_mov_b64_e32 v[168:169], 0
	v_mov_b64_e32 v[170:171], 0
	v_mov_b64_e32 v[172:173], 0
	v_add_co_u32_e32 v212, vcc, 0xffffe000, v210
	s_nop 1
	v_addc_co_u32_e32 v213, vcc, -1, v211, vcc
	v_add_co_u32_e32 v214, vcc, 0x2000, v210
	s_nop 1
	v_addc_co_u32_e32 v215, vcc, 0, v211, vcc
	global_load_dwordx4 v[146:149], v[210:211], off
	global_load_dwordx4 v[150:153], v[210:211], off offset:512
	global_load_dwordx4 v[154:157], v[210:211], off offset:1024
	v_cmp_ne_u32_e32 vcc, 0, v209
	s_and_saveexec_b64 s[0:1], vcc
	global_load_dwordx4 v[158:161], v[212:213], off offset:-1536
	global_load_dwordx4 v[162:165], v[212:213], off offset:-1024
	s_or_b64 exec, exec, s[0:1]
	v_cmp_ne_u32_e32 vcc, s21, v209
	s_and_saveexec_b64 s[0:1], vcc
	global_load_dwordx4 v[166:169], v[214:215], off offset:2560
	global_load_dwordx4 v[170:173], v[214:215], off offset:3072
	s_or_b64 exec, exec, s[0:1]
	s_waitcnt vmcnt(24)
; __device__ __forceinline__ void gmlp_conv_item(const Params& p, int l, int hs, int chunk, LAS unsigned char* lds) {
;     ...
;           unpack8(*(const u32x4*)(rp + OFF_CB), bv); unpack8(*(const u32x4*)(rp + OFF_CC), c1); unpack8(*(const u32x4*)(rp + OFF_CH), h1);
;           { const f32x4 wa = *(const f32x4*)(cw + 256 + cc), wb = *(const f32x4*)(cw + 256 + cc + 4);
; #pragma unroll
;             for (int e = 0; e < 8; ++e) acc[e] = c1[e] * h1[e] * (e < 4 ? wa[e & 3] : wb[e & 3]); }
;           if (pos > 0) { float c0[8], h0[8]; unpack8(*(const u32x4*)(rp - PROJ + OFF_CC), c0); unpack8(*(const u32x4*)(rp - PROJ + OFF_CH), h0);
;               const f32x4 wa = *(const f32x4*)(cw + cc), wb = *(const f32x4*)(cw + cc + 4);
; #pragma unroll
;               for (int e = 0; e < 8; ++e) acc[e] += c0[e] * h0[e] * (e < 4 ? wa[e & 3] : wb[e & 3]); }
;           if (pos < n - 1) { float c2[8], h2[8]; unpack8(*(const u32x4*)(rp + PROJ + OFF_CC), c2); unpack8(*(const u32x4*)(rp + PROJ + OFF_CH), h2);
;               const f32x4 wa = *(const f32x4*)(cw + 512 + cc), wb = *(const f32x4*)(cw + 512 + cc + 4);
; #pragma unroll
;               for (int e = 0; e < 8; ++e) acc[e] += c2[e] * h2[e] * (e < 4 ? wa[e & 3] : wb[e & 3]); }
; #pragma unroll
;           for (int e = 0; e < 8; ++e) acc[e] *= bv[e];
;           *(u32x4*)(Y + (size_t)v * D + cc) = pack8(acc);
	v_lshlrev_b32_e32 v72, 16, v40
	v_and_b32_e32 v73, 0xffff0000, v40
	v_lshlrev_b32_e32 v80, 16, v44
	v_and_b32_e32 v81, 0xffff0000, v44
	v_lshlrev_b32_e32 v74, 16, v41
	v_and_b32_e32 v75, 0xffff0000, v41
	v_lshlrev_b32_e32 v82, 16, v45
	v_and_b32_e32 v83, 0xffff0000, v45
	v_lshlrev_b32_e32 v76, 16, v42
	v_and_b32_e32 v77, 0xffff0000, v42
	v_lshlrev_b32_e32 v84, 16, v46
	v_and_b32_e32 v85, 0xffff0000, v46
	v_lshlrev_b32_e32 v78, 16, v43
	v_and_b32_e32 v79, 0xffff0000, v43
	v_lshlrev_b32_e32 v86, 16, v47
	v_and_b32_e32 v87, 0xffff0000, v47
	v_pk_mul_f32 v[64:65], v[72:73], v[80:81]
	v_pk_mul_f32 v[66:67], v[74:75], v[82:83]
	v_pk_mul_f32 v[68:69], v[76:77], v[84:85]
	v_pk_mul_f32 v[70:71], v[78:79], v[86:87]
	v_pk_mul_f32 v[64:65], v[20:21], v[64:65]
	v_pk_mul_f32 v[66:67], v[22:23], v[66:67]
	v_pk_mul_f32 v[68:69], v[24:25], v[68:69]
	v_pk_mul_f32 v[70:71], v[26:27], v[70:71]
	v_lshlrev_b32_e32 v72, 16, v48
	v_and_b32_e32 v73, 0xffff0000, v48
	v_lshlrev_b32_e32 v80, 16, v52
	v_and_b32_e32 v81, 0xffff0000, v52
	v_lshlrev_b32_e32 v74, 16, v49
	v_and_b32_e32 v75, 0xffff0000, v49
	v_lshlrev_b32_e32 v82, 16, v53
	v_and_b32_e32 v83, 0xffff0000, v53
	v_lshlrev_b32_e32 v76, 16, v50
	v_and_b32_e32 v77, 0xffff0000, v50
	v_lshlrev_b32_e32 v84, 16, v54
	v_and_b32_e32 v85, 0xffff0000, v54
	v_lshlrev_b32_e32 v78, 16, v51
	v_and_b32_e32 v79, 0xffff0000, v51
	v_lshlrev_b32_e32 v86, 16, v55
	v_and_b32_e32 v87, 0xffff0000, v55
	v_pk_mul_f32 v[72:73], v[72:73], v[80:81]
	v_pk_mul_f32 v[74:75], v[74:75], v[82:83]
	v_pk_mul_f32 v[76:77], v[76:77], v[84:85]
	v_pk_mul_f32 v[78:79], v[78:79], v[86:87]
	v_pk_fma_f32 v[64:65], v[12:13], v[72:73], v[64:65]
	v_pk_fma_f32 v[66:67], v[14:15], v[74:75], v[66:67]
	v_pk_fma_f32 v[68:69], v[16:17], v[76:77], v[68:69]
	v_pk_fma_f32 v[70:71], v[18:19], v[78:79], v[70:71]
	v_lshlrev_b32_e32 v72, 16, v56
	v_and_b32_e32 v73, 0xffff0000, v56
	v_lshlrev_b32_e32 v80, 16, v60
	v_and_b32_e32 v81, 0xffff0000, v60
	v_lshlrev_b32_e32 v74, 16, v57
	v_and_b32_e32 v75, 0xffff0000, v57
	v_lshlrev_b32_e32 v82, 16, v61
	v_and_b32_e32 v83, 0xffff0000, v61
	v_lshlrev_b32_e32 v76, 16, v58
	v_and_b32_e32 v77, 0xffff0000, v58
	v_lshlrev_b32_e32 v84, 16, v62
	v_and_b32_e32 v85, 0xffff0000, v62
	v_lshlrev_b32_e32 v78, 16, v59
	v_and_b32_e32 v79, 0xffff0000, v59
	v_lshlrev_b32_e32 v86, 16, v63
	v_and_b32_e32 v87, 0xffff0000, v63
	v_pk_mul_f32 v[72:73], v[72:73], v[80:81]
	v_pk_mul_f32 v[74:75], v[74:75], v[82:83]
	v_pk_mul_f32 v[76:77], v[76:77], v[84:85]
	v_pk_mul_f32 v[78:79], v[78:79], v[86:87]
	v_pk_fma_f32 v[64:65], v[28:29], v[72:73], v[64:65]
	v_pk_fma_f32 v[66:67], v[30:31], v[74:75], v[66:67]
	v_pk_fma_f32 v[68:69], v[32:33], v[76:77], v[68:69]
	v_pk_fma_f32 v[70:71], v[34:35], v[78:79], v[70:71]
	v_lshlrev_b32_e32 v72, 16, v36
	v_and_b32_e32 v73, 0xffff0000, v36
	v_lshlrev_b32_e32 v74, 16, v37
	v_and_b32_e32 v75, 0xffff0000, v37
	v_lshlrev_b32_e32 v76, 16, v38
	v_and_b32_e32 v77, 0xffff0000, v38
	v_lshlrev_b32_e32 v78, 16, v39
	v_and_b32_e32 v79, 0xffff0000, v39
	v_mul_f32_e32 v64, v64, v72
	v_mul_f32_e32 v65, v65, v73
	v_mul_f32_e32 v66, v66, v74
	v_mul_f32_e32 v67, v67, v75
	v_mul_f32_e32 v68, v68, v76
	v_mul_f32_e32 v69, v69, v77
	v_mul_f32_e32 v70, v70, v78
	v_mul_f32_e32 v71, v71, v79
	v_cvt_pk_bf16_f32 v2, v64, v65
	v_cvt_pk_bf16_f32 v3, v66, v67
	v_cvt_pk_bf16_f32 v4, v68, v69
	v_cvt_pk_bf16_f32 v5, v70, v71
	v_lshlrev_b32_e32 v174, 11, v178
	v_lshl_add_u64 v[186:187], v[10:11], 0, v[174:175]
	global_store_dwordx4 v[186:187], v[2:5], off
	s_waitcnt vmcnt(17)
	v_lshlrev_b32_e32 v72, 16, v94
	v_and_b32_e32 v73, 0xffff0000, v94
	v_lshlrev_b32_e32 v80, 16, v98
	v_and_b32_e32 v81, 0xffff0000, v98
	v_lshlrev_b32_e32 v74, 16, v95
	v_and_b32_e32 v75, 0xffff0000, v95
	v_lshlrev_b32_e32 v82, 16, v99
	v_and_b32_e32 v83, 0xffff0000, v99
	v_lshlrev_b32_e32 v76, 16, v96
	v_and_b32_e32 v77, 0xffff0000, v96
	v_lshlrev_b32_e32 v84, 16, v100
	v_and_b32_e32 v85, 0xffff0000, v100
	v_lshlrev_b32_e32 v78, 16, v97
	v_and_b32_e32 v79, 0xffff0000, v97
	v_lshlrev_b32_e32 v86, 16, v101
	v_and_b32_e32 v87, 0xffff0000, v101
	v_pk_mul_f32 v[64:65], v[72:73], v[80:81]
	v_pk_mul_f32 v[66:67], v[74:75], v[82:83]
	v_pk_mul_f32 v[68:69], v[76:77], v[84:85]
	v_pk_mul_f32 v[70:71], v[78:79], v[86:87]
	v_pk_mul_f32 v[64:65], v[20:21], v[64:65]
	v_pk_mul_f32 v[66:67], v[22:23], v[66:67]
	v_pk_mul_f32 v[68:69], v[24:25], v[68:69]
	v_pk_mul_f32 v[70:71], v[26:27], v[70:71]
	v_lshlrev_b32_e32 v72, 16, v102
	v_and_b32_e32 v73, 0xffff0000, v102
	v_lshlrev_b32_e32 v80, 16, v106
	v_and_b32_e32 v81, 0xffff0000, v106
	v_lshlrev_b32_e32 v74, 16, v103
	v_and_b32_e32 v75, 0xffff0000, v103
	v_lshlrev_b32_e32 v82, 16, v107
	v_and_b32_e32 v83, 0xffff0000, v107
	v_lshlrev_b32_e32 v76, 16, v104
	v_and_b32_e32 v77, 0xffff0000, v104
	v_lshlrev_b32_e32 v84, 16, v108
	v_and_b32_e32 v85, 0xffff0000, v108
	v_lshlrev_b32_e32 v78, 16, v105
	v_and_b32_e32 v79, 0xffff0000, v105
	v_lshlrev_b32_e32 v86, 16, v109
	v_and_b32_e32 v87, 0xffff0000, v109
	v_pk_mul_f32 v[72:73], v[72:73], v[80:81]
	v_pk_mul_f32 v[74:75], v[74:75], v[82:83]
	v_pk_mul_f32 v[76:77], v[76:77], v[84:85]
	v_pk_mul_f32 v[78:79], v[78:79], v[86:87]
	v_pk_fma_f32 v[64:65], v[12:13], v[72:73], v[64:65]
	v_pk_fma_f32 v[66:67], v[14:15], v[74:75], v[66:67]
	v_pk_fma_f32 v[68:69], v[16:17], v[76:77], v[68:69]
	v_pk_fma_f32 v[70:71], v[18:19], v[78:79], v[70:71]
	v_lshlrev_b32_e32 v72, 16, v110
	v_and_b32_e32 v73, 0xffff0000, v110
	v_lshlrev_b32_e32 v80, 16, v114
	v_and_b32_e32 v81, 0xffff0000, v114
	v_lshlrev_b32_e32 v74, 16, v111
	v_and_b32_e32 v75, 0xffff0000, v111
	v_lshlrev_b32_e32 v82, 16, v115
	v_and_b32_e32 v83, 0xffff0000, v115
; __device__ __forceinline__ void gmlp_conv_item(const Params& p, int l, int hs, int chunk, LAS unsigned char* lds) {
;     ...
;           unpack8(*(const u32x4*)(rp + OFF_CB), bv); unpack8(*(const u32x4*)(rp + OFF_CC), c1); unpack8(*(const u32x4*)(rp + OFF_CH), h1);
;           { const f32x4 wa = *(const f32x4*)(cw + 256 + cc), wb = *(const f32x4*)(cw + 256 + cc + 4);
; #pragma unroll
;             for (int e = 0; e < 8; ++e) acc[e] = c1[e] * h1[e] * (e < 4 ? wa[e & 3] : wb[e & 3]); }
;           if (pos > 0) { float c0[8], h0[8]; unpack8(*(const u32x4*)(rp - PROJ + OFF_CC), c0); unpack8(*(const u32x4*)(rp - PROJ + OFF_CH), h0);
;               const f32x4 wa = *(const f32x4*)(cw + cc), wb = *(const f32x4*)(cw + cc + 4);
; #pragma unroll
;               for (int e = 0; e < 8; ++e) acc[e] += c0[e] * h0[e] * (e < 4 ? wa[e & 3] : wb[e & 3]); }
;           if (pos < n - 1) { float c2[8], h2[8]; unpack8(*(const u32x4*)(rp + PROJ + OFF_CC), c2); unpack8(*(const u32x4*)(rp + PROJ + OFF_CH), h2);
;               const f32x4 wa = *(const f32x4*)(cw + 512 + cc), wb = *(const f32x4*)(cw + 512 + cc + 4);
; #pragma unroll
;               for (int e = 0; e < 8; ++e) acc[e] += c2[e] * h2[e] * (e < 4 ? wa[e & 3] : wb[e & 3]); }
; #pragma unroll
;           for (int e = 0; e < 8; ++e) acc[e] *= bv[e];
;           *(u32x4*)(Y + (size_t)v * D + cc) = pack8(acc);
	v_lshlrev_b32_e32 v76, 16, v112
	v_and_b32_e32 v77, 0xffff0000, v112
	v_lshlrev_b32_e32 v84, 16, v116
	v_and_b32_e32 v85, 0xffff0000, v116
	v_lshlrev_b32_e32 v78, 16, v113
	v_and_b32_e32 v79, 0xffff0000, v113
	v_lshlrev_b32_e32 v86, 16, v117
	v_and_b32_e32 v87, 0xffff0000, v117
	v_pk_mul_f32 v[72:73], v[72:73], v[80:81]
	v_pk_mul_f32 v[74:75], v[74:75], v[82:83]
	v_pk_mul_f32 v[76:77], v[76:77], v[84:85]
	v_pk_mul_f32 v[78:79], v[78:79], v[86:87]
	v_pk_fma_f32 v[64:65], v[28:29], v[72:73], v[64:65]
	v_pk_fma_f32 v[66:67], v[30:31], v[74:75], v[66:67]
	v_pk_fma_f32 v[68:69], v[32:33], v[76:77], v[68:69]
	v_pk_fma_f32 v[70:71], v[34:35], v[78:79], v[70:71]
	v_lshlrev_b32_e32 v72, 16, v90
	v_and_b32_e32 v73, 0xffff0000, v90
	v_lshlrev_b32_e32 v74, 16, v91
	v_and_b32_e32 v75, 0xffff0000, v91
	v_lshlrev_b32_e32 v76, 16, v92
	v_and_b32_e32 v77, 0xffff0000, v92
	v_lshlrev_b32_e32 v78, 16, v93
	v_and_b32_e32 v79, 0xffff0000, v93
	v_mul_f32_e32 v64, v64, v72
	v_mul_f32_e32 v65, v65, v73
	v_mul_f32_e32 v66, v66, v74
	v_mul_f32_e32 v67, v67, v75
	v_mul_f32_e32 v68, v68, v76
	v_mul_f32_e32 v69, v69, v77
	v_mul_f32_e32 v70, v70, v78
	v_mul_f32_e32 v71, v71, v79
	v_cvt_pk_bf16_f32 v2, v64, v65
	v_cvt_pk_bf16_f32 v3, v66, v67
	v_cvt_pk_bf16_f32 v4, v68, v69
	v_cvt_pk_bf16_f32 v5, v70, v71
	v_lshlrev_b32_e32 v174, 11, v188
	v_lshl_add_u64 v[196:197], v[10:11], 0, v[174:175]
	global_store_dwordx4 v[196:197], v[2:5], off
	s_waitcnt vmcnt(10)
	v_lshlrev_b32_e32 v72, 16, v122
	v_and_b32_e32 v73, 0xffff0000, v122
	v_lshlrev_b32_e32 v80, 16, v126
	v_and_b32_e32 v81, 0xffff0000, v126
	v_lshlrev_b32_e32 v74, 16, v123
	v_and_b32_e32 v75, 0xffff0000, v123
	v_lshlrev_b32_e32 v82, 16, v127
	v_and_b32_e32 v83, 0xffff0000, v127
	v_lshlrev_b32_e32 v76, 16, v124
	v_and_b32_e32 v77, 0xffff0000, v124
	v_lshlrev_b32_e32 v84, 16, v128
	v_and_b32_e32 v85, 0xffff0000, v128
	v_lshlrev_b32_e32 v78, 16, v125
	v_and_b32_e32 v79, 0xffff0000, v125
	v_lshlrev_b32_e32 v86, 16, v129
	v_and_b32_e32 v87, 0xffff0000, v129
	v_pk_mul_f32 v[64:65], v[72:73], v[80:81]
	v_pk_mul_f32 v[66:67], v[74:75], v[82:83]
	v_pk_mul_f32 v[68:69], v[76:77], v[84:85]
	v_pk_mul_f32 v[70:71], v[78:79], v[86:87]
	v_pk_mul_f32 v[64:65], v[20:21], v[64:65]
	v_pk_mul_f32 v[66:67], v[22:23], v[66:67]
	v_pk_mul_f32 v[68:69], v[24:25], v[68:69]
	v_pk_mul_f32 v[70:71], v[26:27], v[70:71]
	v_lshlrev_b32_e32 v72, 16, v130
	v_and_b32_e32 v73, 0xffff0000, v130
	v_lshlrev_b32_e32 v80, 16, v134
	v_and_b32_e32 v81, 0xffff0000, v134
	v_lshlrev_b32_e32 v74, 16, v131
	v_and_b32_e32 v75, 0xffff0000, v131
	v_lshlrev_b32_e32 v82, 16, v135
	v_and_b32_e32 v83, 0xffff0000, v135
	v_lshlrev_b32_e32 v76, 16, v132
	v_and_b32_e32 v77, 0xffff0000, v132
	v_lshlrev_b32_e32 v84, 16, v136
	v_and_b32_e32 v85, 0xffff0000, v136
	v_lshlrev_b32_e32 v78, 16, v133
	v_and_b32_e32 v79, 0xffff0000, v133
	v_lshlrev_b32_e32 v86, 16, v137
	v_and_b32_e32 v87, 0xffff0000, v137
	v_pk_mul_f32 v[72:73], v[72:73], v[80:81]
	v_pk_mul_f32 v[74:75], v[74:75], v[82:83]
	v_pk_mul_f32 v[76:77], v[76:77], v[84:85]
	v_pk_mul_f32 v[78:79], v[78:79], v[86:87]
	v_pk_fma_f32 v[64:65], v[12:13], v[72:73], v[64:65]
	v_pk_fma_f32 v[66:67], v[14:15], v[74:75], v[66:67]
	v_pk_fma_f32 v[68:69], v[16:17], v[76:77], v[68:69]
	v_pk_fma_f32 v[70:71], v[18:19], v[78:79], v[70:71]
	v_lshlrev_b32_e32 v72, 16, v138
	v_and_b32_e32 v73, 0xffff0000, v138
	v_lshlrev_b32_e32 v80, 16, v142
	v_and_b32_e32 v81, 0xffff0000, v142
	v_lshlrev_b32_e32 v74, 16, v139
	v_and_b32_e32 v75, 0xffff0000, v139
	v_lshlrev_b32_e32 v82, 16, v143
	v_and_b32_e32 v83, 0xffff0000, v143
	v_lshlrev_b32_e32 v76, 16, v140
	v_and_b32_e32 v77, 0xffff0000, v140
	v_lshlrev_b32_e32 v84, 16, v144
	v_and_b32_e32 v85, 0xffff0000, v144
	v_lshlrev_b32_e32 v78, 16, v141
	v_and_b32_e32 v79, 0xffff0000, v141
	v_lshlrev_b32_e32 v86, 16, v145
	v_and_b32_e32 v87, 0xffff0000, v145
	v_pk_mul_f32 v[72:73], v[72:73], v[80:81]
	v_pk_mul_f32 v[74:75], v[74:75], v[82:83]
	v_pk_mul_f32 v[76:77], v[76:77], v[84:85]
	v_pk_mul_f32 v[78:79], v[78:79], v[86:87]
	v_pk_fma_f32 v[64:65], v[28:29], v[72:73], v[64:65]
	v_pk_fma_f32 v[66:67], v[30:31], v[74:75], v[66:67]
	v_pk_fma_f32 v[68:69], v[32:33], v[76:77], v[68:69]
	v_pk_fma_f32 v[70:71], v[34:35], v[78:79], v[70:71]
	v_lshlrev_b32_e32 v72, 16, v118
	v_and_b32_e32 v73, 0xffff0000, v118
	v_lshlrev_b32_e32 v74, 16, v119
	v_and_b32_e32 v75, 0xffff0000, v119
	v_lshlrev_b32_e32 v76, 16, v120
	v_and_b32_e32 v77, 0xffff0000, v120
	v_lshlrev_b32_e32 v78, 16, v121
	v_and_b32_e32 v79, 0xffff0000, v121
	v_mul_f32_e32 v64, v64, v72
	v_mul_f32_e32 v65, v65, v73
	v_mul_f32_e32 v66, v66, v74
	v_mul_f32_e32 v67, v67, v75
	v_mul_f32_e32 v68, v68, v76
	v_mul_f32_e32 v69, v69, v77
	v_mul_f32_e32 v70, v70, v78
	v_mul_f32_e32 v71, v71, v79
	v_cvt_pk_bf16_f32 v2, v64, v65
	v_cvt_pk_bf16_f32 v3, v66, v67
	v_cvt_pk_bf16_f32 v4, v68, v69
	v_cvt_pk_bf16_f32 v5, v70, v71
	v_lshlrev_b32_e32 v174, 11, v198
	v_lshl_add_u64 v[206:207], v[10:11], 0, v[174:175]
	global_store_dwordx4 v[206:207], v[2:5], off
	s_waitcnt vmcnt(3)
; __device__ __forceinline__ void gmlp_conv_item(const Params& p, int l, int hs, int chunk, LAS unsigned char* lds) {
;     ...
;           unpack8(*(const u32x4*)(rp + OFF_CB), bv); unpack8(*(const u32x4*)(rp + OFF_CC), c1); unpack8(*(const u32x4*)(rp + OFF_CH), h1);
;           { const f32x4 wa = *(const f32x4*)(cw + 256 + cc), wb = *(const f32x4*)(cw + 256 + cc + 4);
; #pragma unroll
;             for (int e = 0; e < 8; ++e) acc[e] = c1[e] * h1[e] * (e < 4 ? wa[e & 3] : wb[e & 3]); }
;           if (pos > 0) { float c0[8], h0[8]; unpack8(*(const u32x4*)(rp - PROJ + OFF_CC), c0); unpack8(*(const u32x4*)(rp - PROJ + OFF_CH), h0);
;               const f32x4 wa = *(const f32x4*)(cw + cc), wb = *(const f32x4*)(cw + cc + 4);
; #pragma unroll
;               for (int e = 0; e < 8; ++e) acc[e] += c0[e] * h0[e] * (e < 4 ? wa[e & 3] : wb[e & 3]); }
;           if (pos < n - 1) { float c2[8], h2[8]; unpack8(*(const u32x4*)(rp + PROJ + OFF_CC), c2); unpack8(*(const u32x4*)(rp + PROJ + OFF_CH), h2);
;               const f32x4 wa = *(const f32x4*)(cw + 512 + cc), wb = *(const f32x4*)(cw + 512 + cc + 4);
; #pragma unroll
;               for (int e = 0; e < 8; ++e) acc[e] += c2[e] * h2[e] * (e < 4 ? wa[e & 3] : wb[e & 3]); }
; #pragma unroll
;           for (int e = 0; e < 8; ++e) acc[e] *= bv[e];
;           *(u32x4*)(Y + (size_t)v * D + cc) = pack8(acc);
	v_lshlrev_b32_e32 v72, 16, v150
	v_and_b32_e32 v73, 0xffff0000, v150
	v_lshlrev_b32_e32 v80, 16, v154
	v_and_b32_e32 v81, 0xffff0000, v154
	v_lshlrev_b32_e32 v74, 16, v151
	v_and_b32_e32 v75, 0xffff0000, v151
	v_lshlrev_b32_e32 v82, 16, v155
	v_and_b32_e32 v83, 0xffff0000, v155
	v_lshlrev_b32_e32 v76, 16, v152
	v_and_b32_e32 v77, 0xffff0000, v152
	v_lshlrev_b32_e32 v84, 16, v156
	v_and_b32_e32 v85, 0xffff0000, v156
	v_lshlrev_b32_e32 v78, 16, v153
	v_and_b32_e32 v79, 0xffff0000, v153
	v_lshlrev_b32_e32 v86, 16, v157
	v_and_b32_e32 v87, 0xffff0000, v157
	v_pk_mul_f32 v[64:65], v[72:73], v[80:81]
	v_pk_mul_f32 v[66:67], v[74:75], v[82:83]
	v_pk_mul_f32 v[68:69], v[76:77], v[84:85]
	v_pk_mul_f32 v[70:71], v[78:79], v[86:87]
	v_pk_mul_f32 v[64:65], v[20:21], v[64:65]
	v_pk_mul_f32 v[66:67], v[22:23], v[66:67]
	v_pk_mul_f32 v[68:69], v[24:25], v[68:69]
	v_pk_mul_f32 v[70:71], v[26:27], v[70:71]
	v_lshlrev_b32_e32 v72, 16, v158
	v_and_b32_e32 v73, 0xffff0000, v158
	v_lshlrev_b32_e32 v80, 16, v162
	v_and_b32_e32 v81, 0xffff0000, v162
	v_lshlrev_b32_e32 v74, 16, v159
	v_and_b32_e32 v75, 0xffff0000, v159
	v_lshlrev_b32_e32 v82, 16, v163
	v_and_b32_e32 v83, 0xffff0000, v163
	v_lshlrev_b32_e32 v76, 16, v160
	v_and_b32_e32 v77, 0xffff0000, v160
	v_lshlrev_b32_e32 v84, 16, v164
	v_and_b32_e32 v85, 0xffff0000, v164
	v_lshlrev_b32_e32 v78, 16, v161
	v_and_b32_e32 v79, 0xffff0000, v161
	v_lshlrev_b32_e32 v86, 16, v165
	v_and_b32_e32 v87, 0xffff0000, v165
	v_pk_mul_f32 v[72:73], v[72:73], v[80:81]
	v_pk_mul_f32 v[74:75], v[74:75], v[82:83]
	v_pk_mul_f32 v[76:77], v[76:77], v[84:85]
	v_pk_mul_f32 v[78:79], v[78:79], v[86:87]
	v_pk_fma_f32 v[64:65], v[12:13], v[72:73], v[64:65]
	v_pk_fma_f32 v[66:67], v[14:15], v[74:75], v[66:67]
	v_pk_fma_f32 v[68:69], v[16:17], v[76:77], v[68:69]
	v_pk_fma_f32 v[70:71], v[18:19], v[78:79], v[70:71]
	v_lshlrev_b32_e32 v72, 16, v166
	v_and_b32_e32 v73, 0xffff0000, v166
	v_lshlrev_b32_e32 v80, 16, v170
	v_and_b32_e32 v81, 0xffff0000, v170
	v_lshlrev_b32_e32 v74, 16, v167
	v_and_b32_e32 v75, 0xffff0000, v167
	v_lshlrev_b32_e32 v82, 16, v171
	v_and_b32_e32 v83, 0xffff0000, v171
	v_lshlrev_b32_e32 v76, 16, v168
	v_and_b32_e32 v77, 0xffff0000, v168
	v_lshlrev_b32_e32 v84, 16, v172
	v_and_b32_e32 v85, 0xffff0000, v172
	v_lshlrev_b32_e32 v78, 16, v169
	v_and_b32_e32 v79, 0xffff0000, v169
	v_lshlrev_b32_e32 v86, 16, v173
	v_and_b32_e32 v87, 0xffff0000, v173
	v_pk_mul_f32 v[72:73], v[72:73], v[80:81]
	v_pk_mul_f32 v[74:75], v[74:75], v[82:83]
	v_pk_mul_f32 v[76:77], v[76:77], v[84:85]
	v_pk_mul_f32 v[78:79], v[78:79], v[86:87]
	v_pk_fma_f32 v[64:65], v[28:29], v[72:73], v[64:65]
	v_pk_fma_f32 v[66:67], v[30:31], v[74:75], v[66:67]
	v_pk_fma_f32 v[68:69], v[32:33], v[76:77], v[68:69]
	v_pk_fma_f32 v[70:71], v[34:35], v[78:79], v[70:71]
	v_lshlrev_b32_e32 v72, 16, v146
	v_and_b32_e32 v73, 0xffff0000, v146
	v_lshlrev_b32_e32 v74, 16, v147
	v_and_b32_e32 v75, 0xffff0000, v147
	v_lshlrev_b32_e32 v76, 16, v148
	v_and_b32_e32 v77, 0xffff0000, v148
	v_lshlrev_b32_e32 v78, 16, v149
	v_and_b32_e32 v79, 0xffff0000, v149
	v_mul_f32_e32 v64, v64, v72
	v_mul_f32_e32 v65, v65, v73
	v_mul_f32_e32 v66, v66, v74
	v_mul_f32_e32 v67, v67, v75
	v_mul_f32_e32 v68, v68, v76
	v_mul_f32_e32 v69, v69, v77
	v_mul_f32_e32 v70, v70, v78
	v_mul_f32_e32 v71, v71, v79
	v_cvt_pk_bf16_f32 v2, v64, v65
	v_cvt_pk_bf16_f32 v3, v66, v67
	v_cvt_pk_bf16_f32 v4, v68, v69
	v_cvt_pk_bf16_f32 v5, v70, v71
	v_lshlrev_b32_e32 v174, 11, v208
	v_lshl_add_u64 v[216:217], v[10:11], 0, v[174:175]
	global_store_dwordx4 v[216:217], v[2:5], off
	s_movk_i32 s22, 0x1000
	s_branch .LBB0_173
